# E27: E23 + mixer A/B/D score tiles start from inline-constant zero accumulator (first MFMA srcC=0, 16 zeroing v_mov per tile deleted)
# speedup vs baseline: 1.0074x; 1.0074x over previous
; template <class MB> __device__ __forceinline__ void la_soft(LA& st, f32x16& s, const TP& t, bf16x8& pf0, bf16x8& pf1) {
;     float mx = NEGBIG;
; #pragma unroll
;     for (int r = 0; r < 16; ++r) { s[r] = MB::apply(t, r, s[r]); mx = __builtin_fmaxf(mx, s[r]); }
;     { auto rr = __builtin_amdgcn_permlane32_swap(__float_as_uint(mx), __float_as_uint(mx), false, false); mx = __builtin_fmaxf(__uint_as_float(rr[0]), __uint_as_float(rr[1])); }
;     if (__any(mx > st.m)) { const float mn = __builtin_fmaxf(st.m, mx), alpha = __builtin_amdgcn_exp2f(st.m - mn); st.m = mn; st.l *= alpha; st.o0 *= alpha; st.o1 *= alpha; }
; template <class MB, int V1, class VS> __device__ __forceinline__ void la_step2(LA& sa, LA& sb, const bf16x8 (&qa)[4], const bf16x8 (&qb)[4], Frag& f, const char* kb, const VS& vs, const TP& t, const TP& n) {
;     bf16x8 pa0, pa1;
;     { f32x16 s0 = zero16();
; #pragma unroll
;       for (int d0 = 0; d0 < 4; ++d0) s0 = __builtin_amdgcn_mfma_f32_32x32x16_bf16(f.k[d0], qa[d0], s0, 0, 0, 0);
;       la_soft<MB>(sa, s0, t, pa0, pa1); }
.LBB0_661:
	s_add_i32 s4, s7, s9
	s_addk_i32 s4, 0xffa0
	s_cmpk_lt_u32 s4, 0x4000
	v_lshl_add_u32 v64, v64, 1, v148
	s_cselect_b64 s[4:5], -1, 0
	s_cmpk_lg_i32 s9, 0xc0
	v_add_u32_e32 v65, 0x9000, v64
	s_cselect_b64 s[10:11], -1, 0
	ds_read_b128 v[136:139], v65 offset:41472
	ds_read_b128 v[128:131], v65 offset:41504
	ds_read_b128 v[140:143], v64 offset:36864
	ds_read_b128 v[132:135], v64 offset:36896
	s_and_b64 vcc, s[10:11], s[4:5]
	v_add_u32_e32 v150, 0x80, v152
	v_mov_b32_e32 v64, s53
	v_cndmask_b32_e32 v167, v64, v150, vcc
	ds_read2_b32 v[154:155], v167 offset1:1
	s_waitcnt vmcnt(3)
	s_nop 0
	v_mfma_f32_32x32x16_bf16 v[64:79], v[124:127], v[96:99], 0
	s_waitcnt vmcnt(2)
	v_mfma_f32_32x32x16_bf16 v[64:79], v[120:123], v[88:91], v[64:79]
	s_waitcnt vmcnt(1)
	v_mfma_f32_32x32x16_bf16 v[64:79], v[116:119], v[92:95], v[64:79]
	s_waitcnt vmcnt(0)
	v_mfma_f32_32x32x16_bf16 v[64:79], v[112:115], v[100:103], v[64:79]
	s_waitcnt lgkmcnt(0)
	s_nop 10
	v_add_f32_e32 v154, v64, v154
	v_add_f32_e32 v153, v65, v155
	ds_read2_b32 v[64:65], v167 offset0:2 offset1:3
	v_max3_f32 v157, v154, s2, v153
	s_waitcnt lgkmcnt(0)
	v_add_f32_e32 v156, v66, v64
	v_add_f32_e32 v155, v67, v65
	ds_read2_b32 v[64:65], v167 offset0:4 offset1:5
	v_max3_f32 v66, v157, v156, v155
	s_waitcnt lgkmcnt(0)
	v_add_f32_e32 v158, v68, v64
	v_add_f32_e32 v157, v69, v65
	ds_read2_b32 v[64:65], v167 offset0:6 offset1:7
	v_max3_f32 v66, v66, v158, v157
	s_waitcnt lgkmcnt(0)
	v_add_f32_e32 v160, v70, v64
	v_add_f32_e32 v159, v71, v65
	ds_read2_b32 v[64:65], v167 offset0:16 offset1:17
	v_max3_f32 v66, v66, v160, v159
	s_waitcnt lgkmcnt(0)
	v_add_f32_e32 v162, v72, v64
	v_add_f32_e32 v161, v73, v65
	ds_read2_b32 v[64:65], v167 offset0:18 offset1:19
	v_max3_f32 v66, v66, v162, v161
	s_waitcnt lgkmcnt(0)
	v_add_f32_e32 v166, v74, v64
	v_add_f32_e32 v165, v75, v65
	ds_read2_b32 v[64:65], v167 offset0:20 offset1:21
	v_max3_f32 v66, v66, v166, v165
	s_waitcnt lgkmcnt(0)
	v_add_f32_e32 v164, v76, v64
	v_add_f32_e32 v163, v77, v65
	ds_read2_b32 v[64:65], v167 offset0:22 offset1:23
	v_max3_f32 v66, v66, v164, v163
	s_waitcnt lgkmcnt(0)
	v_add_f32_e32 v168, v78, v64
	v_add_f32_e32 v167, v79, v65
	v_max3_f32 v64, v66, v168, v167
	v_mov_b32_e32 v65, v64
	s_nop 1
	v_permlane32_swap_b32_e32 v64, v65
	v_max_f32_e32 v65, v65, v65
	v_max_f32_e32 v64, v64, v64
	v_max_f32_e32 v64, v64, v65
	v_cmp_gt_f32_e32 vcc, v64, v151
	s_cbranch_vccz .LBB0_663
	v_max_f32_e32 v64, v64, v64
	v_max_f32_e32 v65, v151, v151
	v_max_f32_e32 v65, v65, v64
	v_sub_f32_e32 v64, v151, v65
	v_exp_f32_e32 v64, v64
	v_mov_b32_e32 v151, v65
	v_mul_f32_e32 v147, v64, v147
	v_pk_mul_f32 v[46:47], v[64:65], v[46:47] op_sel_hi:[0,1]
	v_pk_mul_f32 v[44:45], v[64:65], v[44:45] op_sel_hi:[0,1]
	v_pk_mul_f32 v[42:43], v[64:65], v[42:43] op_sel_hi:[0,1]
	v_pk_mul_f32 v[40:41], v[64:65], v[40:41] op_sel_hi:[0,1]
	v_pk_mul_f32 v[38:39], v[64:65], v[38:39] op_sel_hi:[0,1]
	v_pk_mul_f32 v[36:37], v[64:65], v[36:37] op_sel_hi:[0,1]
	v_pk_mul_f32 v[34:35], v[64:65], v[34:35] op_sel_hi:[0,1]
	v_pk_mul_f32 v[32:33], v[64:65], v[32:33] op_sel_hi:[0,1]
	v_pk_mul_f32 v[62:63], v[64:65], v[62:63] op_sel_hi:[0,1]
	v_pk_mul_f32 v[60:61], v[64:65], v[60:61] op_sel_hi:[0,1]
	v_pk_mul_f32 v[58:59], v[64:65], v[58:59] op_sel_hi:[0,1]
	v_pk_mul_f32 v[56:57], v[64:65], v[56:57] op_sel_hi:[0,1]
	v_pk_mul_f32 v[54:55], v[64:65], v[54:55] op_sel_hi:[0,1]
	v_pk_mul_f32 v[52:53], v[64:65], v[52:53] op_sel_hi:[0,1]
	v_pk_mul_f32 v[50:51], v[64:65], v[50:51] op_sel_hi:[0,1]
	v_pk_mul_f32 v[48:49], v[64:65], v[48:49] op_sel_hi:[0,1]
; __device__ __forceinline__ unsigned cvt_pk_bf16(float lo, float hi) { f32x2_c v = {lo, hi}; bf16x2_c b = __builtin_convertvector(v, bf16x2_c); return __builtin_bit_cast(unsigned, b); }
; template <class MB> __device__ __forceinline__ void la_soft(LA& st, f32x16& s, const TP& t, bf16x8& pf0, bf16x8& pf1) {
;     ...
;     float rs = 0.f;
; #pragma unroll
;     for (int r = 0; r < 16; ++r) { s[r] = __builtin_amdgcn_exp2f(s[r] - st.m); rs += s[r]; }
;     st.l += rs;
;     u32x4 p0, p1;
; #pragma unroll
;     for (int e = 0; e < 4; ++e) { p0[e] = cvt_pk_bf16(s[2 * e], s[2 * e + 1]); p1[e] = cvt_pk_bf16(s[8 + 2 * e], s[8 + 2 * e + 1]); }
;     pf0 = __builtin_bit_cast(bf16x8, p0); pf1 = __builtin_bit_cast(bf16x8, p1);
; template <class MB, int V1, class VS> __device__ __forceinline__ void la_step2(LA& sa, LA& sb, const bf16x8 (&qa)[4], const bf16x8 (&qb)[4], Frag& f, const char* kb, const VS& vs, const TP& t, const TP& n) {
;     ...
;     f32x16 s1 = zero16();
; #pragma unroll
;     for (int d0 = 0; d0 < 4; ++d0) s1 = __builtin_amdgcn_mfma_f32_32x32x16_bf16(f.k[d0], qb[d0], s1, 0, 0, 0);
;     la_loadK(f, kb, n);
;     sa.o0 = __builtin_amdgcn_mfma_f32_32x32x16_bf16(f.v[0], pa0, sa.o0, 0, 0, 0); sa.o1 = __builtin_amdgcn_mfma_f32_32x32x16_bf16(f.v[2], pa0, sa.o1, 0, 0, 0);
;     sa.o0 = __builtin_amdgcn_mfma_f32_32x32x16_bf16(f.v[1], pa1, sa.o0, 0, 0, 0); sa.o1 = __builtin_amdgcn_mfma_f32_32x32x16_bf16(f.v[3], pa1, sa.o1, 0, 0, 0);
;     { bf16x8 pb0, pb1; const TP tb = MB::second(t);
;       la_soft<MB>(sb, s1, tb, pb0, pb1);
.LBB0_663:
	s_cmp_lg_u32 s9, 32
	s_cselect_b64 s[10:11], -1, 0
	s_and_b64 vcc, s[10:11], s[4:5]
	s_cmpk_lg_i32 s9, 0xc0
	s_cselect_b32 s4, s9, 0xa0
	s_add_i32 s5, s8, s4
	s_cmpk_lt_u32 s5, 0x4000
	s_cselect_b32 s5, s5, s7
	v_or_b32_e32 v64, s5, v185
	v_mul_lo_u32 v64, v64, s67
	v_add_lshl_u32 v175, v64, v181, 1
	v_mov_b32_e32 v174, s53
	v_cndmask_b32_e32 v180, v174, v152, vcc
	s_nop 0
	v_mfma_f32_32x32x16_bf16 v[64:79], v[124:127], v[80:83], 0
	v_sub_f32_e32 v124, v154, v151
	v_exp_f32_e32 v154, v124
	v_sub_f32_e32 v124, v153, v151
	v_exp_f32_e32 v153, v124
	v_sub_f32_e32 v124, v156, v151
	v_exp_f32_e32 v156, v124
	v_sub_f32_e32 v124, v155, v151
	v_mfma_f32_32x32x16_bf16 v[64:79], v[120:123], v[84:87], v[64:79]
	v_sub_f32_e32 v120, v158, v151
	v_exp_f32_e32 v158, v120
	v_sub_f32_e32 v120, v157, v151
	v_exp_f32_e32 v157, v120
	v_sub_f32_e32 v120, v160, v151
	v_exp_f32_e32 v155, v124
	v_exp_f32_e32 v160, v120
	v_mfma_f32_32x32x16_bf16 v[64:79], v[116:119], v[104:107], v[64:79]
	v_sub_f32_e32 v116, v159, v151
	v_exp_f32_e32 v159, v116
	v_sub_f32_e32 v116, v162, v151
	v_exp_f32_e32 v162, v116
	v_sub_f32_e32 v116, v161, v151
	v_exp_f32_e32 v161, v116
	v_sub_f32_e32 v116, v166, v151
	v_exp_f32_e32 v166, v116
	v_sub_f32_e32 v116, v164, v151
	v_exp_f32_e32 v164, v116
	v_sub_f32_e32 v116, v163, v151
	v_mfma_f32_32x32x16_bf16 v[64:79], v[112:115], v[108:111], v[64:79]
	v_sub_f32_e32 v112, v165, v151
	v_exp_f32_e32 v169, v116
	v_sub_f32_e32 v116, v168, v151
	v_exp_f32_e32 v165, v112
	v_cvt_pk_bf16_f32 v112, v154, v153
	v_cvt_pk_bf16_f32 v113, v156, v155
	v_cvt_pk_bf16_f32 v114, v158, v157
	v_cvt_pk_bf16_f32 v115, v160, v159
	v_exp_f32_e32 v168, v116
	v_sub_f32_e32 v116, v167, v151
	v_mfma_f32_32x32x16_bf16 v[32:47], v[140:143], v[112:115], v[32:47]
	v_exp_f32_e32 v163, v116
	global_load_dwordx4 v[124:127], v175, s[74:75]
	global_load_dwordx4 v[120:123], v175, s[74:75] offset:32
	v_cvt_pk_bf16_f32 v170, v162, v161
	v_cvt_pk_bf16_f32 v171, v166, v165
	v_cvt_pk_bf16_f32 v172, v164, v169
	v_cvt_pk_bf16_f32 v173, v168, v163
	v_mfma_f32_32x32x16_bf16 v[48:63], v[136:139], v[112:115], v[48:63]
	global_load_dwordx4 v[116:119], v175, s[74:75] offset:64
	global_load_dwordx4 v[112:115], v175, s[74:75] offset:96
	ds_read2_b32 v[174:175], v180 offset1:1
	ds_read2_b32 v[176:177], v180 offset0:2 offset1:3
	ds_read2_b32 v[178:179], v180 offset0:4 offset1:5
	ds_read2_b32 v[182:183], v180 offset0:6 offset1:7
	s_waitcnt lgkmcnt(3)
	v_add_f32_e32 v174, v64, v174
	v_mfma_f32_32x32x16_bf16 v[32:47], v[132:135], v[170:173], v[32:47]
	s_waitcnt lgkmcnt(1)
	v_add_f32_e32 v167, v68, v178
	v_add_f32_e32 v152, v69, v179
	s_waitcnt lgkmcnt(0)
	v_add_f32_e32 v70, v70, v182
	v_add_f32_e32 v69, v71, v183
	v_mfma_f32_32x32x16_bf16 v[48:63], v[128:131], v[170:173], v[48:63]
	v_add_f32_e32 v173, v65, v175
	v_max3_f32 v64, v174, s2, v173
	v_add_f32_e32 v171, v66, v176
	v_add_f32_e32 v170, v67, v177
	v_max3_f32 v64, v64, v171, v170
	v_max3_f32 v66, v64, v167, v152
	ds_read2_b32 v[64:65], v180 offset0:16 offset1:17
	v_max3_f32 v68, v66, v70, v69
	ds_read2_b32 v[66:67], v180 offset0:18 offset1:19
	ds_read2_b32 v[176:177], v180 offset0:20 offset1:21
	ds_read2_b32 v[178:179], v180 offset0:22 offset1:23
	s_waitcnt lgkmcnt(3)
	v_add_f32_e32 v172, v72, v64
	v_add_f32_e32 v72, v73, v65
	v_max3_f32 v64, v68, v172, v72
	s_waitcnt lgkmcnt(2)
	v_add_f32_e32 v71, v74, v66
	v_add_f32_e32 v67, v75, v67
	v_max3_f32 v64, v64, v71, v67
	s_waitcnt lgkmcnt(1)
	v_add_f32_e32 v68, v76, v176
	v_add_f32_e32 v65, v77, v177
	v_max3_f32 v73, v64, v68, v65
	s_waitcnt lgkmcnt(0)
	v_add_f32_e32 v66, v78, v178
	v_add_f32_e32 v64, v79, v179
	v_max3_f32 v73, v73, v66, v64
	v_mov_b32_e32 v74, v73
	s_nop 1
	v_permlane32_swap_b32_e32 v73, v74
	v_max_f32_e32 v74, v74, v74
	v_max_f32_e32 v73, v73, v73
	v_max_f32_e32 v73, v73, v74
	v_cmp_gt_f32_e32 vcc, v73, v145
	s_cbranch_vccz .LBB0_665
	v_max_f32_e32 v73, v73, v73
	v_max_f32_e32 v74, v145, v145
	v_max_f32_e32 v73, v74, v73
	v_sub_f32_e32 v74, v145, v73
	v_exp_f32_e32 v74, v74
	v_mov_b32_e32 v145, v73
	v_mul_f32_e32 v144, v74, v144
	v_pk_mul_f32 v[14:15], v[74:75], v[14:15] op_sel_hi:[0,1]
	v_pk_mul_f32 v[12:13], v[74:75], v[12:13] op_sel_hi:[0,1]
	v_pk_mul_f32 v[10:11], v[74:75], v[10:11] op_sel_hi:[0,1]
	v_pk_mul_f32 v[8:9], v[74:75], v[8:9] op_sel_hi:[0,1]
	v_pk_mul_f32 v[6:7], v[74:75], v[6:7] op_sel_hi:[0,1]
	v_pk_mul_f32 v[4:5], v[74:75], v[4:5] op_sel_hi:[0,1]
	v_pk_mul_f32 v[2:3], v[74:75], v[2:3] op_sel_hi:[0,1]
	v_pk_mul_f32 v[0:1], v[74:75], v[0:1] op_sel_hi:[0,1]
	v_pk_mul_f32 v[30:31], v[74:75], v[30:31] op_sel_hi:[0,1]
	v_pk_mul_f32 v[28:29], v[74:75], v[28:29] op_sel_hi:[0,1]
	v_pk_mul_f32 v[26:27], v[74:75], v[26:27] op_sel_hi:[0,1]
	v_pk_mul_f32 v[24:25], v[74:75], v[24:25] op_sel_hi:[0,1]
	v_pk_mul_f32 v[22:23], v[74:75], v[22:23] op_sel_hi:[0,1]
	v_pk_mul_f32 v[20:21], v[74:75], v[20:21] op_sel_hi:[0,1]
	v_pk_mul_f32 v[18:19], v[74:75], v[18:19] op_sel_hi:[0,1]
	v_pk_mul_f32 v[16:17], v[74:75], v[16:17] op_sel_hi:[0,1]

; template <class MB> __device__ __forceinline__ void la_soft(LA& st, f32x16& s, const TP& t, bf16x8& pf0, bf16x8& pf1) {
;     float mx = NEGBIG;
; #pragma unroll
;     for (int r = 0; r < 16; ++r) { s[r] = MB::apply(t, r, s[r]); mx = __builtin_fmaxf(mx, s[r]); }
;     { auto rr = __builtin_amdgcn_permlane32_swap(__float_as_uint(mx), __float_as_uint(mx), false, false); mx = __builtin_fmaxf(__uint_as_float(rr[0]), __uint_as_float(rr[1])); }
;     if (__any(mx > st.m)) { const float mn = __builtin_fmaxf(st.m, mx), alpha = __builtin_amdgcn_exp2f(st.m - mn); st.m = mn; st.l *= alpha; st.o0 *= alpha; st.o1 *= alpha; }
; template <class MB, int V1, class VS> __device__ __forceinline__ void la_step2(LA& sa, LA& sb, const bf16x8 (&qa)[4], const bf16x8 (&qb)[4], Frag& f, const char* kb, const VS& vs, const TP& t, const TP& n) {
;     bf16x8 pa0, pa1;
;     { f32x16 s0 = zero16();
; #pragma unroll
;       for (int d0 = 0; d0 < 4; ++d0) s0 = __builtin_amdgcn_mfma_f32_32x32x16_bf16(f.k[d0], qa[d0], s0, 0, 0, 0);
;       la_soft<MB>(sa, s0, t, pa0, pa1); }
.LBB0_673:
	v_lshlrev_b32_e32 v64, 1, v73
	v_ashrrev_i32_e32 v65, 31, v64
	v_lshl_add_u64 v[64:65], s[6:7], 0, v[64:65]
	v_add_co_u32_e32 v66, vcc, s80, v64
	s_add_i32 s8, s11, s13
	s_nop 0
	v_addc_co_u32_e32 v67, vcc, 0, v65, vcc
	global_load_dwordx4 v[128:131], v[66:67], off offset:2080
	global_load_dwordx4 v[136:139], v[66:67], off offset:2048
	global_load_dwordx4 v[132:135], v[64:65], off offset:32
	global_load_dwordx4 v[140:143], v[64:65], off
	s_cmpk_lt_u32 s8, 0x4000
	s_cselect_b64 s[8:9], -1, 0
	s_cmpk_lg_i32 s12, 0x480
	s_cselect_b64 s[14:15], -1, 0
	v_add_u32_e32 v197, s12, v195
	s_and_b64 vcc, s[14:15], s[8:9]
	v_add_u32_e32 v64, 0x80, v197
	v_mov_b32_e32 v65, s53
	v_cndmask_b32_e32 v212, v65, v64, vcc
	ds_read2_b32 v[200:201], v212 offset1:1
	s_waitcnt vmcnt(7)
	s_nop 0
	v_mfma_f32_32x32x16_bf16 v[64:79], v[124:127], v[80:83], 0
	s_waitcnt vmcnt(6)
	v_mfma_f32_32x32x16_bf16 v[64:79], v[120:123], v[84:87], v[64:79]
	s_waitcnt vmcnt(5)
	v_mfma_f32_32x32x16_bf16 v[64:79], v[116:119], v[96:99], v[64:79]
	s_waitcnt vmcnt(4)
	v_mfma_f32_32x32x16_bf16 v[64:79], v[112:115], v[100:103], v[64:79]
	s_waitcnt lgkmcnt(0)
	s_nop 10
	v_add_f32_e32 v199, v64, v200
	v_add_f32_e32 v198, v65, v201
	ds_read2_b32 v[64:65], v212 offset0:2 offset1:3
	v_max3_f32 v202, v199, s2, v198
	s_waitcnt lgkmcnt(0)
	v_add_f32_e32 v201, v66, v64
	v_add_f32_e32 v200, v67, v65
	ds_read2_b32 v[64:65], v212 offset0:4 offset1:5
	v_max3_f32 v66, v202, v201, v200
	s_waitcnt lgkmcnt(0)
	v_add_f32_e32 v203, v68, v64
	v_add_f32_e32 v202, v69, v65
	ds_read2_b32 v[64:65], v212 offset0:6 offset1:7
	v_max3_f32 v66, v66, v203, v202
	s_waitcnt lgkmcnt(0)
	v_add_f32_e32 v205, v70, v64
	v_add_f32_e32 v204, v71, v65
	ds_read2_b32 v[64:65], v212 offset0:16 offset1:17
	v_max3_f32 v66, v66, v205, v204
	s_waitcnt lgkmcnt(0)
	v_add_f32_e32 v207, v72, v64
	v_add_f32_e32 v206, v73, v65
	ds_read2_b32 v[64:65], v212 offset0:18 offset1:19
	v_max3_f32 v66, v66, v207, v206
	s_waitcnt lgkmcnt(0)
	v_add_f32_e32 v211, v74, v64
	v_add_f32_e32 v210, v75, v65
	ds_read2_b32 v[64:65], v212 offset0:20 offset1:21
	v_max3_f32 v66, v66, v211, v210
	s_waitcnt lgkmcnt(0)
	v_add_f32_e32 v209, v76, v64
	v_add_f32_e32 v208, v77, v65
	ds_read2_b32 v[64:65], v212 offset0:22 offset1:23
	v_max3_f32 v66, v66, v209, v208
	s_waitcnt lgkmcnt(0)
	v_add_f32_e32 v213, v78, v64
	v_add_f32_e32 v212, v79, v65
	v_max3_f32 v64, v66, v213, v212
	v_mov_b32_e32 v65, v64
	s_nop 1
	v_permlane32_swap_b32_e32 v64, v65
	v_max_f32_e32 v65, v65, v65
	v_max_f32_e32 v64, v64, v64
	v_max_f32_e32 v64, v64, v65
	v_cmp_gt_f32_e32 vcc, v64, v196
	s_cbranch_vccz .LBB0_675
	v_max_f32_e32 v64, v64, v64
	v_max_f32_e32 v65, v196, v196
	v_max_f32_e32 v65, v65, v64
	v_sub_f32_e32 v64, v196, v65
	v_exp_f32_e32 v64, v64
	v_mov_b32_e32 v196, v65
	v_mul_f32_e32 v193, v193, v64
	v_pk_mul_f32 v[62:63], v[62:63], v[64:65] op_sel_hi:[1,0]
	v_pk_mul_f32 v[60:61], v[60:61], v[64:65] op_sel_hi:[1,0]
	v_pk_mul_f32 v[58:59], v[58:59], v[64:65] op_sel_hi:[1,0]
	v_pk_mul_f32 v[56:57], v[56:57], v[64:65] op_sel_hi:[1,0]
	v_pk_mul_f32 v[54:55], v[54:55], v[64:65] op_sel_hi:[1,0]
	v_pk_mul_f32 v[52:53], v[52:53], v[64:65] op_sel_hi:[1,0]
	v_pk_mul_f32 v[50:51], v[50:51], v[64:65] op_sel_hi:[1,0]
	v_pk_mul_f32 v[48:49], v[48:49], v[64:65] op_sel_hi:[1,0]
	v_pk_mul_f32 v[46:47], v[46:47], v[64:65] op_sel_hi:[1,0]
	v_pk_mul_f32 v[44:45], v[44:45], v[64:65] op_sel_hi:[1,0]
	v_pk_mul_f32 v[42:43], v[42:43], v[64:65] op_sel_hi:[1,0]
	v_pk_mul_f32 v[40:41], v[40:41], v[64:65] op_sel_hi:[1,0]
	v_pk_mul_f32 v[38:39], v[38:39], v[64:65] op_sel_hi:[1,0]
	v_pk_mul_f32 v[36:37], v[36:37], v[64:65] op_sel_hi:[1,0]
	v_pk_mul_f32 v[34:35], v[34:35], v[64:65] op_sel_hi:[1,0]
	v_pk_mul_f32 v[32:33], v[32:33], v[64:65] op_sel_hi:[1,0]
; __device__ __forceinline__ unsigned cvt_pk_bf16(float lo, float hi) { f32x2_c v = {lo, hi}; bf16x2_c b = __builtin_convertvector(v, bf16x2_c); return __builtin_bit_cast(unsigned, b); }
; template <class MB> __device__ __forceinline__ void la_soft(LA& st, f32x16& s, const TP& t, bf16x8& pf0, bf16x8& pf1) {
;     ...
;     float rs = 0.f;
; #pragma unroll
;     for (int r = 0; r < 16; ++r) { s[r] = __builtin_amdgcn_exp2f(s[r] - st.m); rs += s[r]; }
;     st.l += rs;
;     u32x4 p0, p1;
; #pragma unroll
;     for (int e = 0; e < 4; ++e) { p0[e] = cvt_pk_bf16(s[2 * e], s[2 * e + 1]); p1[e] = cvt_pk_bf16(s[8 + 2 * e], s[8 + 2 * e + 1]); }
;     pf0 = __builtin_bit_cast(bf16x8, p0); pf1 = __builtin_bit_cast(bf16x8, p1);
; template <class MB, int V1, class VS> __device__ __forceinline__ void la_step2(LA& sa, LA& sb, const bf16x8 (&qa)[4], const bf16x8 (&qb)[4], Frag& f, const char* kb, const VS& vs, const TP& t, const TP& n) {
;     ...
;     f32x16 s1 = zero16();
; #pragma unroll
;     for (int d0 = 0; d0 < 4; ++d0) s1 = __builtin_amdgcn_mfma_f32_32x32x16_bf16(f.k[d0], qb[d0], s1, 0, 0, 0);
;     la_loadK(f, kb, n);
;     sa.o0 = __builtin_amdgcn_mfma_f32_32x32x16_bf16(f.v[0], pa0, sa.o0, 0, 0, 0); sa.o1 = __builtin_amdgcn_mfma_f32_32x32x16_bf16(f.v[2], pa0, sa.o1, 0, 0, 0);
;     sa.o0 = __builtin_amdgcn_mfma_f32_32x32x16_bf16(f.v[1], pa1, sa.o0, 0, 0, 0); sa.o1 = __builtin_amdgcn_mfma_f32_32x32x16_bf16(f.v[3], pa1, sa.o1, 0, 0, 0);
;     { bf16x8 pb0, pb1; const TP tb = MB::second(t);
;       la_soft<MB>(sb, s1, tb, pb0, pb1);
.LBB0_675:
	s_cmp_lg_u32 s12, 0
	s_cselect_b64 s[14:15], -1, 0
	s_and_b64 vcc, s[14:15], s[8:9]
	s_add_i32 s13, s13, 32
	s_cmpk_lg_i32 s12, 0x480
	s_cselect_b32 s8, s13, 0xa0
	s_add_i32 s8, s8, s11
	s_cmpk_lt_u32 s8, 0x4000
	s_cselect_b32 s8, s8, s11
	v_or_b32_e32 v64, s8, v185
	v_mul_lo_u32 v64, v64, s67
	v_add_lshl_u32 v219, v64, v192, 1
	v_mov_b32_e32 v218, s53
	v_cndmask_b32_e32 v226, v218, v197, vcc
	s_nop 0
	v_mfma_f32_32x32x16_bf16 v[64:79], v[124:127], v[88:91], 0
	v_sub_f32_e32 v124, v199, v196
	v_exp_f32_e32 v199, v124
	v_sub_f32_e32 v124, v198, v196
	v_exp_f32_e32 v198, v124
	v_sub_f32_e32 v124, v201, v196
	v_exp_f32_e32 v201, v124
	v_sub_f32_e32 v124, v200, v196
	v_mfma_f32_32x32x16_bf16 v[64:79], v[120:123], v[92:95], v[64:79]
	v_sub_f32_e32 v120, v203, v196
	v_exp_f32_e32 v203, v120
	v_sub_f32_e32 v120, v202, v196
	v_exp_f32_e32 v202, v120
	v_sub_f32_e32 v120, v205, v196
	v_exp_f32_e32 v200, v124
	v_exp_f32_e32 v205, v120
	v_mfma_f32_32x32x16_bf16 v[64:79], v[116:119], v[104:107], v[64:79]
	v_sub_f32_e32 v116, v204, v196
	v_exp_f32_e32 v204, v116
	v_sub_f32_e32 v116, v207, v196
	v_exp_f32_e32 v207, v116
	v_sub_f32_e32 v116, v206, v196
	v_exp_f32_e32 v206, v116
	v_sub_f32_e32 v116, v211, v196
	v_exp_f32_e32 v211, v116
	v_sub_f32_e32 v116, v209, v196
	v_exp_f32_e32 v209, v116
	v_sub_f32_e32 v116, v208, v196
	v_mfma_f32_32x32x16_bf16 v[64:79], v[112:115], v[108:111], v[64:79]
	v_sub_f32_e32 v112, v210, v196
	v_exp_f32_e32 v208, v116
	v_sub_f32_e32 v116, v213, v196
	v_exp_f32_e32 v210, v112
	v_cvt_pk_bf16_f32 v112, v199, v198
	v_cvt_pk_bf16_f32 v113, v201, v200
	v_cvt_pk_bf16_f32 v114, v203, v202
	v_cvt_pk_bf16_f32 v115, v205, v204
	v_exp_f32_e32 v213, v116
	v_sub_f32_e32 v116, v212, v196
	s_waitcnt vmcnt(0)
	v_mfma_f32_32x32x16_bf16 v[48:63], v[140:143], v[112:115], v[48:63]
	v_exp_f32_e32 v212, v116
	global_load_dwordx4 v[124:127], v219, s[74:75]
	global_load_dwordx4 v[120:123], v219, s[74:75] offset:32
	v_cvt_pk_bf16_f32 v214, v207, v206
	v_cvt_pk_bf16_f32 v215, v211, v210
	v_cvt_pk_bf16_f32 v216, v209, v208
	v_cvt_pk_bf16_f32 v217, v213, v212
	v_mfma_f32_32x32x16_bf16 v[32:47], v[136:139], v[112:115], v[32:47]
	global_load_dwordx4 v[116:119], v219, s[74:75] offset:64
	global_load_dwordx4 v[112:115], v219, s[74:75] offset:96
	ds_read2_b32 v[220:221], v226 offset1:1
	s_waitcnt lgkmcnt(0)
	v_add_f32_e32 v219, v64, v220
	v_mfma_f32_32x32x16_bf16 v[48:63], v[132:135], v[214:217], v[48:63]
	v_add_f32_e32 v218, v65, v221
	v_max3_f32 v64, v219, s2, v218
	v_mfma_f32_32x32x16_bf16 v[32:47], v[128:131], v[214:217], v[32:47]
	ds_read2_b32 v[214:215], v226 offset0:2 offset1:3
	ds_read2_b32 v[222:223], v226 offset0:4 offset1:5
	ds_read2_b32 v[224:225], v226 offset0:6 offset1:7
	s_waitcnt lgkmcnt(2)
	v_add_f32_e32 v216, v66, v214
	v_add_f32_e32 v215, v67, v215
	v_max3_f32 v64, v64, v216, v215
	s_waitcnt lgkmcnt(1)
	v_add_f32_e32 v214, v68, v222
	v_add_f32_e32 v197, v69, v223
	v_max3_f32 v66, v64, v214, v197
	ds_read2_b32 v[64:65], v226 offset0:16 offset1:17
	s_waitcnt lgkmcnt(1)
	v_add_f32_e32 v69, v70, v224
	v_add_f32_e32 v68, v71, v225
	v_max3_f32 v70, v66, v69, v68
	ds_read2_b32 v[66:67], v226 offset0:18 offset1:19
	ds_read2_b32 v[220:221], v226 offset0:20 offset1:21
	ds_read2_b32 v[222:223], v226 offset0:22 offset1:23
	s_waitcnt lgkmcnt(3)
	v_add_f32_e32 v217, v72, v64
	v_add_f32_e32 v72, v73, v65
	v_max3_f32 v64, v70, v217, v72
	s_waitcnt lgkmcnt(2)
	v_add_f32_e32 v71, v74, v66
	v_add_f32_e32 v70, v75, v67
	v_max3_f32 v64, v64, v71, v70
	s_waitcnt lgkmcnt(1)
	v_add_f32_e32 v67, v76, v220
	v_add_f32_e32 v65, v77, v221
	v_max3_f32 v73, v64, v67, v65
	s_waitcnt lgkmcnt(0)
	v_add_f32_e32 v66, v78, v222
	v_add_f32_e32 v64, v79, v223
	v_max3_f32 v73, v73, v66, v64
	v_mov_b32_e32 v74, v73
	s_nop 1
	v_permlane32_swap_b32_e32 v73, v74
	v_max_f32_e32 v74, v74, v74
	v_max_f32_e32 v73, v73, v73
	v_max_f32_e32 v73, v73, v74
	v_cmp_gt_f32_e32 vcc, v73, v191
	s_cbranch_vccz .LBB0_672
	v_max_f32_e32 v73, v73, v73
	v_max_f32_e32 v74, v191, v191
	v_max_f32_e32 v73, v74, v73
	v_sub_f32_e32 v74, v191, v73
	v_exp_f32_e32 v74, v74
	v_mov_b32_e32 v191, v73
	v_mul_f32_e32 v190, v190, v74
	v_pk_mul_f32 v[30:31], v[30:31], v[74:75] op_sel_hi:[1,0]
	v_pk_mul_f32 v[28:29], v[28:29], v[74:75] op_sel_hi:[1,0]
	v_pk_mul_f32 v[26:27], v[26:27], v[74:75] op_sel_hi:[1,0]
	v_pk_mul_f32 v[24:25], v[24:25], v[74:75] op_sel_hi:[1,0]
	v_pk_mul_f32 v[22:23], v[22:23], v[74:75] op_sel_hi:[1,0]
	v_pk_mul_f32 v[20:21], v[20:21], v[74:75] op_sel_hi:[1,0]
	v_pk_mul_f32 v[18:19], v[18:19], v[74:75] op_sel_hi:[1,0]
	v_pk_mul_f32 v[16:17], v[16:17], v[74:75] op_sel_hi:[1,0]
	v_pk_mul_f32 v[14:15], v[14:15], v[74:75] op_sel_hi:[1,0]
	v_pk_mul_f32 v[12:13], v[12:13], v[74:75] op_sel_hi:[1,0]
	v_pk_mul_f32 v[10:11], v[10:11], v[74:75] op_sel_hi:[1,0]
	v_pk_mul_f32 v[8:9], v[8:9], v[74:75] op_sel_hi:[1,0]
	v_pk_mul_f32 v[6:7], v[6:7], v[74:75] op_sel_hi:[1,0]
	v_pk_mul_f32 v[4:5], v[4:5], v[74:75] op_sel_hi:[1,0]
	v_pk_mul_f32 v[2:3], v[2:3], v[74:75] op_sel_hi:[1,0]
	v_pk_mul_f32 v[0:1], v[0:1], v[74:75] op_sel_hi:[1,0]
	s_branch .LBB0_672

; template <class MB> __device__ __forceinline__ void la_soft(LA& st, f32x16& s, const TP& t, bf16x8& pf0, bf16x8& pf1) {
;     float mx = NEGBIG;
; #pragma unroll
;     for (int r = 0; r < 16; ++r) { s[r] = MB::apply(t, r, s[r]); mx = __builtin_fmaxf(mx, s[r]); }
;     { auto rr = __builtin_amdgcn_permlane32_swap(__float_as_uint(mx), __float_as_uint(mx), false, false); mx = __builtin_fmaxf(__uint_as_float(rr[0]), __uint_as_float(rr[1])); }
;     if (__any(mx > st.m)) { const float mn = __builtin_fmaxf(st.m, mx), alpha = __builtin_amdgcn_exp2f(st.m - mn); st.m = mn; st.l *= alpha; st.o0 *= alpha; st.o1 *= alpha; }
; template <class MB, int V1, class VS> __device__ __forceinline__ void la_step2(LA& sa, LA& sb, const bf16x8 (&qa)[4], const bf16x8 (&qb)[4], Frag& f, const char* kb, const VS& vs, const TP& t, const TP& n) {
;     bf16x8 pa0, pa1;
;     { f32x16 s0 = zero16();
; #pragma unroll
;       for (int d0 = 0; d0 < 4; ++d0) s0 = __builtin_amdgcn_mfma_f32_32x32x16_bf16(f.k[d0], qa[d0], s0, 0, 0, 0);
;       la_soft<MB>(sa, s0, t, pa0, pa1); }
.LBB0_678:
	v_lshl_add_u32 v64, s41, 2, v165
	v_ashrrev_i32_e32 v65, 31, v64
	v_lshl_add_u64 v[64:65], s[56:57], 0, v[64:65]
	v_add_co_u32_e32 v66, vcc, s80, v64
	s_cmp_eq_u32 s60, 8
	s_nop 0
	v_addc_co_u32_e32 v67, vcc, 0, v65, vcc
	global_load_dwordx4 v[128:131], v[66:67], off offset:2080
	global_load_dwordx4 v[136:139], v[66:67], off offset:2048
	global_load_dwordx4 v[132:135], v[64:65], off offset:32
	global_load_dwordx4 v[140:143], v[64:65], off
	s_cselect_b64 s[40:41], -1, 0
	v_add_u32_e32 v166, 0x200, v167
	v_mov_b32_e32 v64, s53
	v_cndmask_b32_e64 v183, v166, v64, s[40:41]
	ds_read2_b32 v[168:169], v183 offset1:1
	s_waitcnt vmcnt(7)
	s_nop 0
	v_mfma_f32_32x32x16_bf16 v[64:79], v[124:127], v[96:99], 0
	s_waitcnt vmcnt(6)
	v_mfma_f32_32x32x16_bf16 v[64:79], v[120:123], v[100:103], v[64:79]
	s_waitcnt vmcnt(5)
	v_mfma_f32_32x32x16_bf16 v[64:79], v[116:119], v[104:107], v[64:79]
	s_waitcnt vmcnt(4)
	v_mfma_f32_32x32x16_bf16 v[64:79], v[112:115], v[108:111], v[64:79]
	s_waitcnt lgkmcnt(0)
	s_nop 10
	v_add_f32_e32 v64, v64, v168
	v_cndmask_b32_e64 v168, v232, v64, s[6:7]
	v_add_f32_e32 v64, v65, v169
	v_cndmask_b32_e64 v169, v232, v64, s[8:9]
	ds_read2_b32 v[64:65], v183 offset0:2 offset1:3
	v_max3_f32 v172, v168, s2, v169
	s_waitcnt lgkmcnt(0)
	v_add_f32_e32 v64, v66, v64
	v_cndmask_b32_e64 v170, v232, v64, s[10:11]
	v_add_f32_e32 v64, v67, v65
	v_cndmask_b32_e64 v171, v232, v64, s[12:13]
	ds_read2_b32 v[64:65], v183 offset0:4 offset1:5
	v_max3_f32 v66, v172, v170, v171
	s_waitcnt lgkmcnt(0)
	v_add_f32_e32 v64, v68, v64
	v_cndmask_b32_e64 v172, v232, v64, s[14:15]
	v_add_f32_e32 v64, v69, v65
	v_cndmask_b32_e64 v173, v232, v64, s[16:17]
	ds_read2_b32 v[64:65], v183 offset0:6 offset1:7
	v_max3_f32 v66, v66, v172, v173
	s_waitcnt lgkmcnt(0)
	v_add_f32_e32 v64, v70, v64
	v_cndmask_b32_e64 v175, v232, v64, s[18:19]
	v_add_f32_e32 v64, v71, v65
	v_cndmask_b32_e64 v174, v232, v64, s[20:21]
	ds_read2_b32 v[64:65], v183 offset0:16 offset1:17
	v_max3_f32 v66, v66, v175, v174
	s_waitcnt lgkmcnt(0)
	v_add_f32_e32 v64, v72, v64
	v_cndmask_b32_e64 v176, v232, v64, s[22:23]
	v_add_f32_e32 v64, v73, v65
	v_cndmask_b32_e64 v177, v232, v64, s[24:25]
	ds_read2_b32 v[64:65], v183 offset0:18 offset1:19
	v_max3_f32 v66, v66, v176, v177
	s_waitcnt lgkmcnt(0)
	v_add_f32_e32 v64, v74, v64
	v_cndmask_b32_e64 v179, v232, v64, s[26:27]
	v_add_f32_e32 v64, v75, v65
	v_cndmask_b32_e64 v178, v232, v64, s[28:29]
	ds_read2_b32 v[64:65], v183 offset0:20 offset1:21
	v_max3_f32 v66, v66, v179, v178
	s_waitcnt lgkmcnt(0)
	v_add_f32_e32 v64, v76, v64
	v_cndmask_b32_e64 v180, v232, v64, s[30:31]
	v_add_f32_e32 v64, v77, v65
	v_cndmask_b32_e64 v182, v232, v64, s[34:35]
	ds_read2_b32 v[64:65], v183 offset0:22 offset1:23
	v_max3_f32 v66, v66, v180, v182
	s_waitcnt lgkmcnt(0)
	v_add_f32_e32 v64, v78, v64
	v_cndmask_b32_e64 v183, v232, v64, s[36:37]
	v_add_f32_e32 v64, v79, v65
	v_cndmask_b32_e64 v190, v232, v64, s[38:39]
	v_max3_f32 v64, v66, v183, v190
	v_mov_b32_e32 v65, v64
	s_nop 1
	v_permlane32_swap_b32_e32 v64, v65
	v_max_f32_e32 v65, v65, v65
	v_max_f32_e32 v64, v64, v64
	v_max_f32_e32 v64, v64, v65
	v_cmp_gt_f32_e32 vcc, v64, v162
	s_cbranch_vccz .LBB0_680
	v_max_f32_e32 v64, v64, v64
	v_max_f32_e32 v65, v162, v162
	v_max_f32_e32 v65, v65, v64
	v_sub_f32_e32 v64, v162, v65
	v_exp_f32_e32 v64, v64
	v_mov_b32_e32 v162, v65
	v_mul_f32_e32 v157, v157, v64
	v_pk_mul_f32 v[62:63], v[62:63], v[64:65] op_sel_hi:[1,0]
	v_pk_mul_f32 v[60:61], v[60:61], v[64:65] op_sel_hi:[1,0]
	v_pk_mul_f32 v[58:59], v[58:59], v[64:65] op_sel_hi:[1,0]
	v_pk_mul_f32 v[56:57], v[56:57], v[64:65] op_sel_hi:[1,0]
	v_pk_mul_f32 v[54:55], v[54:55], v[64:65] op_sel_hi:[1,0]
	v_pk_mul_f32 v[52:53], v[52:53], v[64:65] op_sel_hi:[1,0]
	v_pk_mul_f32 v[50:51], v[50:51], v[64:65] op_sel_hi:[1,0]
	v_pk_mul_f32 v[48:49], v[48:49], v[64:65] op_sel_hi:[1,0]
	v_pk_mul_f32 v[46:47], v[46:47], v[64:65] op_sel_hi:[1,0]
	v_pk_mul_f32 v[44:45], v[44:45], v[64:65] op_sel_hi:[1,0]
	v_pk_mul_f32 v[42:43], v[42:43], v[64:65] op_sel_hi:[1,0]
	v_pk_mul_f32 v[40:41], v[40:41], v[64:65] op_sel_hi:[1,0]
	v_pk_mul_f32 v[38:39], v[38:39], v[64:65] op_sel_hi:[1,0]
	v_pk_mul_f32 v[36:37], v[36:37], v[64:65] op_sel_hi:[1,0]
	v_pk_mul_f32 v[34:35], v[34:35], v[64:65] op_sel_hi:[1,0]
	v_pk_mul_f32 v[32:33], v[32:33], v[64:65] op_sel_hi:[1,0]
; __device__ __forceinline__ unsigned cvt_pk_bf16(float lo, float hi) { f32x2_c v = {lo, hi}; bf16x2_c b = __builtin_convertvector(v, bf16x2_c); return __builtin_bit_cast(unsigned, b); }
; template <class MB> __device__ __forceinline__ void la_soft(LA& st, f32x16& s, const TP& t, bf16x8& pf0, bf16x8& pf1) {
;     ...
;     float rs = 0.f;
; #pragma unroll
;     for (int r = 0; r < 16; ++r) { s[r] = __builtin_amdgcn_exp2f(s[r] - st.m); rs += s[r]; }
;     st.l += rs;
;     u32x4 p0, p1;
; #pragma unroll
;     for (int e = 0; e < 4; ++e) { p0[e] = cvt_pk_bf16(s[2 * e], s[2 * e + 1]); p1[e] = cvt_pk_bf16(s[8 + 2 * e], s[8 + 2 * e + 1]); }
;     pf0 = __builtin_bit_cast(bf16x8, p0); pf1 = __builtin_bit_cast(bf16x8, p1);
; template <class MB, int V1, class VS> __device__ __forceinline__ void la_step2(LA& sa, LA& sb, const bf16x8 (&qa)[4], const bf16x8 (&qb)[4], Frag& f, const char* kb, const VS& vs, const TP& t, const TP& n) {
;     ...
;     f32x16 s1 = zero16();
; #pragma unroll
;     for (int d0 = 0; d0 < 4; ++d0) s1 = __builtin_amdgcn_mfma_f32_32x32x16_bf16(f.k[d0], qb[d0], s1, 0, 0, 0);
;     la_loadK(f, kb, n);
;     sa.o0 = __builtin_amdgcn_mfma_f32_32x32x16_bf16(f.v[0], pa0, sa.o0, 0, 0, 0); sa.o1 = __builtin_amdgcn_mfma_f32_32x32x16_bf16(f.v[2], pa0, sa.o1, 0, 0, 0);
;     sa.o0 = __builtin_amdgcn_mfma_f32_32x32x16_bf16(f.v[1], pa1, sa.o0, 0, 0, 0); sa.o1 = __builtin_amdgcn_mfma_f32_32x32x16_bf16(f.v[3], pa1, sa.o1, 0, 0, 0);
;     { bf16x8 pb0, pb1; const TP tb = MB::second(t);
;       la_soft<MB>(sb, s1, tb, pb0, pb1);
.LBB0_680:
	s_add_i32 s0, s59, s60
	v_cmp_ge_u32_e32 vcc, s0, v159
	v_cmp_lt_u32_e64 s[44:45], s0, v153
	s_and_b64 vcc, vcc, s[44:45]
	s_add_i32 s60, s60, 1
	s_and_b64 s[40:41], s[40:41], exec
	s_cselect_b32 s0, 8, s60
	s_add_i32 s0, s0, s59
	s_min_i32 s0, s0, 0xff
	s_lshl_b32 s0, s0, 6
	s_or_b32 s41, s0, s55
	v_or_b32_e32 v64, s41, v185
	v_mul_lo_u32 v64, v64, s67
	v_add_lshl_u32 v196, v64, v161, 1
	v_mov_b32_e32 v191, s53
	v_cndmask_b32_e32 v204, v191, v167, vcc
	s_nop 0
	v_mfma_f32_32x32x16_bf16 v[64:79], v[124:127], v[80:83], 0
	v_sub_f32_e32 v124, v168, v162
	v_exp_f32_e32 v168, v124
	v_sub_f32_e32 v124, v169, v162
	v_exp_f32_e32 v169, v124
	v_sub_f32_e32 v124, v170, v162
	v_exp_f32_e32 v170, v124
	v_sub_f32_e32 v124, v171, v162
	v_mfma_f32_32x32x16_bf16 v[64:79], v[120:123], v[84:87], v[64:79]
	v_sub_f32_e32 v120, v172, v162
	v_exp_f32_e32 v172, v120
	v_sub_f32_e32 v120, v173, v162
	v_exp_f32_e32 v173, v120
	v_sub_f32_e32 v120, v175, v162
	v_exp_f32_e32 v171, v124
	v_exp_f32_e32 v175, v120
	v_mfma_f32_32x32x16_bf16 v[64:79], v[116:119], v[88:91], v[64:79]
	v_sub_f32_e32 v116, v174, v162
	v_exp_f32_e32 v174, v116
	v_sub_f32_e32 v116, v176, v162
	v_exp_f32_e32 v176, v116
	v_sub_f32_e32 v116, v177, v162
	v_exp_f32_e32 v177, v116
	v_sub_f32_e32 v116, v179, v162
	v_exp_f32_e32 v179, v116
	v_sub_f32_e32 v116, v180, v162
	v_exp_f32_e32 v180, v116
	v_sub_f32_e32 v116, v182, v162
	v_mfma_f32_32x32x16_bf16 v[64:79], v[112:115], v[92:95], v[64:79]
	v_sub_f32_e32 v112, v178, v162
	v_exp_f32_e32 v182, v116
	v_sub_f32_e32 v116, v183, v162
	v_exp_f32_e32 v178, v112
	v_cvt_pk_bf16_f32 v112, v168, v169
	v_cvt_pk_bf16_f32 v113, v170, v171
	v_cvt_pk_bf16_f32 v114, v172, v173
	v_cvt_pk_bf16_f32 v115, v175, v174
	v_exp_f32_e32 v183, v116
	v_sub_f32_e32 v116, v190, v162
	s_waitcnt vmcnt(0)
	v_mfma_f32_32x32x16_bf16 v[48:63], v[140:143], v[112:115], v[48:63]
	v_exp_f32_e32 v190, v116
	global_load_dwordx4 v[124:127], v196, s[74:75]
	global_load_dwordx4 v[120:123], v196, s[74:75] offset:32
	v_cvt_pk_bf16_f32 v192, v176, v177
	v_cvt_pk_bf16_f32 v193, v179, v178
	v_cvt_pk_bf16_f32 v194, v180, v182
	v_cvt_pk_bf16_f32 v195, v183, v190
	v_mfma_f32_32x32x16_bf16 v[32:47], v[136:139], v[112:115], v[32:47]
	global_load_dwordx4 v[116:119], v196, s[74:75] offset:64
	global_load_dwordx4 v[112:115], v196, s[74:75] offset:96
	ds_read2_b32 v[196:197], v204 offset1:1
	ds_read2_b32 v[198:199], v204 offset0:2 offset1:3
	ds_read2_b32 v[200:201], v204 offset0:4 offset1:5
	ds_read2_b32 v[202:203], v204 offset0:6 offset1:7
	s_waitcnt lgkmcnt(3)
	v_add_f32_e32 v64, v64, v196
	v_mfma_f32_32x32x16_bf16 v[48:63], v[132:135], v[192:195], v[48:63]
	v_mfma_f32_32x32x16_bf16 v[32:47], v[128:131], v[192:195], v[32:47]
	v_cndmask_b32_e64 v195, v232, v64, s[6:7]
	v_add_f32_e32 v64, v65, v197
	s_waitcnt lgkmcnt(2)
	v_add_f32_e32 v65, v66, v198
	v_cndmask_b32_e64 v194, v232, v65, s[10:11]
	v_add_f32_e32 v65, v67, v199
	v_cndmask_b32_e64 v193, v232, v64, s[8:9]
	v_cndmask_b32_e64 v191, v232, v65, s[12:13]
	s_waitcnt lgkmcnt(1)
	v_add_f32_e32 v65, v68, v200
	v_max3_f32 v64, v195, s2, v193
	v_cndmask_b32_e64 v192, v232, v65, s[14:15]
	v_add_f32_e32 v65, v69, v201
	v_max3_f32 v64, v64, v194, v191
	v_cndmask_b32_e64 v167, v232, v65, s[16:17]
	v_max3_f32 v66, v64, v192, v167
	s_waitcnt lgkmcnt(0)
	v_add_f32_e32 v64, v70, v202
	v_cndmask_b32_e64 v70, v232, v64, s[18:19]
	v_add_f32_e32 v64, v71, v203
	v_cndmask_b32_e64 v69, v232, v64, s[20:21]
	ds_read2_b32 v[64:65], v204 offset0:16 offset1:17
	v_max3_f32 v68, v66, v70, v69
	ds_read2_b32 v[66:67], v204 offset0:18 offset1:19
	ds_read2_b32 v[198:199], v204 offset0:20 offset1:21
	ds_read2_b32 v[200:201], v204 offset0:22 offset1:23
	s_waitcnt lgkmcnt(3)
	v_add_f32_e32 v64, v72, v64
	v_cndmask_b32_e64 v196, v232, v64, s[22:23]
	v_add_f32_e32 v64, v73, v65
	v_cndmask_b32_e64 v71, v232, v64, s[24:25]
	s_waitcnt lgkmcnt(2)
	v_add_f32_e32 v64, v74, v66
	v_cndmask_b32_e64 v72, v232, v64, s[26:27]
	v_add_f32_e32 v64, v75, v67
	v_max3_f32 v65, v68, v196, v71
	v_cndmask_b32_e64 v64, v232, v64, s[28:29]
	s_waitcnt lgkmcnt(1)
	v_add_f32_e32 v66, v76, v198
	v_add_f32_e32 v67, v77, v199
	v_max3_f32 v65, v65, v72, v64
	v_cndmask_b32_e64 v66, v232, v66, s[30:31]
	v_cndmask_b32_e64 v67, v232, v67, s[34:35]
	v_max3_f32 v73, v65, v66, v67
	s_waitcnt lgkmcnt(0)
	v_add_f32_e32 v65, v78, v200
	v_cndmask_b32_e64 v68, v232, v65, s[36:37]
	v_add_f32_e32 v65, v79, v201
	v_cndmask_b32_e64 v65, v232, v65, s[38:39]
	v_max3_f32 v73, v73, v68, v65
	v_mov_b32_e32 v74, v73
	s_nop 1
	v_permlane32_swap_b32_e32 v73, v74
	v_max_f32_e32 v74, v74, v74
	v_max_f32_e32 v73, v73, v73
	v_max_f32_e32 v73, v73, v74
	v_cmp_gt_f32_e32 vcc, v73, v145
	s_cbranch_vccz .LBB0_682
	v_max_f32_e32 v73, v73, v73
	v_max_f32_e32 v74, v145, v145
	v_max_f32_e32 v73, v74, v73
	v_sub_f32_e32 v74, v145, v73
	v_exp_f32_e32 v74, v74
	v_mov_b32_e32 v145, v73
	v_mul_f32_e32 v156, v156, v74
	v_pk_mul_f32 v[30:31], v[30:31], v[74:75] op_sel_hi:[1,0]
	v_pk_mul_f32 v[28:29], v[28:29], v[74:75] op_sel_hi:[1,0]
	v_pk_mul_f32 v[26:27], v[26:27], v[74:75] op_sel_hi:[1,0]
	v_pk_mul_f32 v[24:25], v[24:25], v[74:75] op_sel_hi:[1,0]
	v_pk_mul_f32 v[22:23], v[22:23], v[74:75] op_sel_hi:[1,0]
	v_pk_mul_f32 v[20:21], v[20:21], v[74:75] op_sel_hi:[1,0]
	v_pk_mul_f32 v[18:19], v[18:19], v[74:75] op_sel_hi:[1,0]
	v_pk_mul_f32 v[16:17], v[16:17], v[74:75] op_sel_hi:[1,0]
	v_pk_mul_f32 v[14:15], v[14:15], v[74:75] op_sel_hi:[1,0]
	v_pk_mul_f32 v[12:13], v[12:13], v[74:75] op_sel_hi:[1,0]
	v_pk_mul_f32 v[10:11], v[10:11], v[74:75] op_sel_hi:[1,0]
	v_pk_mul_f32 v[8:9], v[8:9], v[74:75] op_sel_hi:[1,0]
	v_pk_mul_f32 v[6:7], v[6:7], v[74:75] op_sel_hi:[1,0]
	v_pk_mul_f32 v[4:5], v[4:5], v[74:75] op_sel_hi:[1,0]
	v_pk_mul_f32 v[2:3], v[2:3], v[74:75] op_sel_hi:[1,0]
	v_pk_mul_f32 v[0:1], v[0:1], v[74:75] op_sel_hi:[1,0]

; template <class MB, int V1, class VS> __device__ __forceinline__ void la_step(LA& st, const bf16x8 (&qf)[4], Frag& f, const char* kb, const VS& vs, const TP& t, const TP& n) {
;     f32x16 s = zero16();
; #pragma unroll
;     for (int d0 = 0; d0 < 4; ++d0) s = __builtin_amdgcn_mfma_f32_32x32x16_bf16(f.k[d0], qf[d0], s, 0, 0, 0);
;     la_loadK(f, kb, n);
;     float mx = NEGBIG;
; #pragma unroll
;     for (int r = 0; r < 16; ++r) { s[r] = MB::apply(t, r, s[r]); mx = __builtin_fmaxf(mx, s[r]); }
;     { auto rr = __builtin_amdgcn_permlane32_swap(__float_as_uint(mx), __float_as_uint(mx), false, false); mx = __builtin_fmaxf(__uint_as_float(rr[0]), __uint_as_float(rr[1])); }
;     if (__any(mx > st.m)) { const float mn = __builtin_fmaxf(st.m, mx), alpha = __builtin_amdgcn_exp2f(st.m - mn); st.m = mn; st.l *= alpha; st.o0 *= alpha; st.o1 *= alpha; }
.LBB0_685:
	v_or_b32_e32 v64, v64, v184
	v_lshl_or_b32 v64, v64, 7, s0
	v_add_lshl_u32 v64, v64, v164, 1
	v_ashrrev_i32_e32 v65, 31, v64
	v_lshl_add_u64 v[64:65], s[56:57], 0, v[64:65]
	v_add_co_u32_e32 v66, vcc, s80, v64
	v_add_u32_e32 v170, s24, v166
	s_nop 0
	v_addc_co_u32_e32 v67, vcc, 0, v65, vcc
	global_load_dwordx4 v[128:131], v[66:67], off offset:2560
	global_load_dwordx4 v[132:135], v[66:67], off offset:2048
	global_load_dwordx4 v[136:139], v[64:65], off offset:512
	global_load_dwordx4 v[140:143], v[64:65], off
	v_add_u32_e32 v167, 0x7120, v170
	s_waitcnt vmcnt(7)
	s_nop 0
	v_mfma_f32_32x32x16_bf16 v[64:79], v[112:115], v[96:99], 0
	s_waitcnt vmcnt(6)
	v_mfma_f32_32x32x16_bf16 v[64:79], v[120:123], v[100:103], v[64:79]
	s_waitcnt vmcnt(5)
	v_mfma_f32_32x32x16_bf16 v[64:79], v[116:119], v[104:107], v[64:79]
	s_waitcnt vmcnt(4)
	v_mfma_f32_32x32x16_bf16 v[64:79], v[124:127], v[108:111], v[64:79]
	global_load_dwordx4 v[112:115], v[152:153], off
	global_load_dwordx4 v[120:123], v[152:153], off offset:32
	global_load_dwordx4 v[116:119], v[152:153], off offset:64
	global_load_dwordx4 v[124:127], v[152:153], off offset:96
	ds_read2_b32 v[168:169], v167 offset1:1
	s_waitcnt lgkmcnt(0)
	s_nop 5
	v_add_f32_e32 v64, v64, v168
	v_cndmask_b32_e64 v167, v232, v64, s[6:7]
	v_add_f32_e32 v64, v65, v169
	v_add_u32_e32 v65, 0x7128, v170
	ds_read2_b32 v[168:169], v65 offset1:1
	v_cndmask_b32_e64 v64, v232, v64, s[8:9]
	v_max3_f32 v171, v167, s2, v64
	s_waitcnt lgkmcnt(0)
	v_add_f32_e32 v65, v66, v168
	v_cndmask_b32_e64 v66, v232, v65, s[10:11]
	v_add_f32_e32 v65, v67, v169
	v_add_u32_e32 v67, 0x7130, v170
	ds_read2_b32 v[168:169], v67 offset1:1
	v_cndmask_b32_e64 v65, v232, v65, s[12:13]
	v_max3_f32 v171, v171, v66, v65
	s_waitcnt lgkmcnt(0)
	v_add_f32_e32 v67, v68, v168
	v_cndmask_b32_e64 v68, v232, v67, s[14:15]
	v_add_f32_e32 v67, v69, v169
	v_add_u32_e32 v69, 0x7138, v170
	ds_read2_b32 v[168:169], v69 offset1:1
	v_cndmask_b32_e64 v67, v232, v67, s[16:17]
	v_max3_f32 v171, v171, v68, v67
	s_waitcnt lgkmcnt(0)
	v_add_f32_e32 v69, v70, v168
	v_cndmask_b32_e64 v70, v232, v69, s[18:19]
	v_add_f32_e32 v69, v71, v169
	v_add_u32_e32 v71, 0x7520, v170
	ds_read2_b32 v[168:169], v71 offset1:1
	v_cndmask_b32_e64 v69, v232, v69, s[20:21]
	v_max3_f32 v171, v171, v70, v69
	s_waitcnt lgkmcnt(0)
	v_add_f32_e32 v71, v72, v168
	v_cndmask_b32_e64 v72, v232, v71, s[6:7]
	v_add_f32_e32 v71, v73, v169
	v_add_u32_e32 v73, 0x7528, v170
	ds_read2_b32 v[168:169], v73 offset1:1
	v_cndmask_b32_e64 v71, v232, v71, s[8:9]
	v_max3_f32 v171, v171, v72, v71
	s_waitcnt lgkmcnt(0)
	v_add_f32_e32 v73, v74, v168
	v_cndmask_b32_e64 v74, v232, v73, s[10:11]
	v_add_f32_e32 v73, v75, v169
	v_add_u32_e32 v75, 0x7530, v170
	ds_read2_b32 v[168:169], v75 offset1:1
	v_cndmask_b32_e64 v73, v232, v73, s[12:13]
	v_max3_f32 v171, v171, v74, v73
	s_waitcnt lgkmcnt(0)
	v_add_f32_e32 v75, v76, v168
	v_cndmask_b32_e64 v76, v232, v75, s[14:15]
	v_add_f32_e32 v75, v77, v169
	v_add_u32_e32 v77, 0x7538, v170
	ds_read2_b32 v[168:169], v77 offset1:1
	v_cndmask_b32_e64 v75, v232, v75, s[16:17]
	v_max3_f32 v171, v171, v76, v75
	s_waitcnt lgkmcnt(0)
	v_add_f32_e32 v77, v78, v168
	v_cndmask_b32_e64 v78, v232, v77, s[18:19]
	v_add_f32_e32 v77, v79, v169
	v_cndmask_b32_e64 v77, v232, v77, s[20:21]
	v_max3_f32 v79, v171, v78, v77
	v_mov_b32_e32 v168, v79
	s_nop 1
	v_permlane32_swap_b32_e32 v79, v168
	v_max_f32_e32 v168, v168, v168
	v_max_f32_e32 v79, v79, v79
	v_max_f32_e32 v79, v79, v168
	v_cmp_gt_f32_e32 vcc, v79, v162
	s_cbranch_vccz .LBB0_687
	v_max_f32_e32 v79, v79, v79
	v_max_f32_e32 v168, v162, v162
	v_max_f32_e32 v79, v168, v79
	v_sub_f32_e32 v162, v162, v79
	v_exp_f32_e32 v162, v162
	s_nop 0
	v_mul_f32_e32 v157, v157, v162
	v_pk_mul_f32 v[62:63], v[62:63], v[162:163] op_sel_hi:[1,0]
	v_pk_mul_f32 v[60:61], v[60:61], v[162:163] op_sel_hi:[1,0]
	v_pk_mul_f32 v[58:59], v[58:59], v[162:163] op_sel_hi:[1,0]
	v_pk_mul_f32 v[56:57], v[56:57], v[162:163] op_sel_hi:[1,0]
	v_pk_mul_f32 v[54:55], v[54:55], v[162:163] op_sel_hi:[1,0]
	v_pk_mul_f32 v[52:53], v[52:53], v[162:163] op_sel_hi:[1,0]
	v_pk_mul_f32 v[50:51], v[50:51], v[162:163] op_sel_hi:[1,0]
	v_pk_mul_f32 v[48:49], v[48:49], v[162:163] op_sel_hi:[1,0]
	v_pk_mul_f32 v[46:47], v[46:47], v[162:163] op_sel_hi:[1,0]
	v_pk_mul_f32 v[44:45], v[44:45], v[162:163] op_sel_hi:[1,0]
	v_pk_mul_f32 v[42:43], v[42:43], v[162:163] op_sel_hi:[1,0]
	v_pk_mul_f32 v[40:41], v[40:41], v[162:163] op_sel_hi:[1,0]
	v_pk_mul_f32 v[38:39], v[38:39], v[162:163] op_sel_hi:[1,0]
	v_pk_mul_f32 v[36:37], v[36:37], v[162:163] op_sel_hi:[1,0]
	v_pk_mul_f32 v[34:35], v[34:35], v[162:163] op_sel_hi:[1,0]
	v_pk_mul_f32 v[32:33], v[32:33], v[162:163] op_sel_hi:[1,0]
	v_mov_b32_e32 v162, v79

; template <class MB, int V1, class VS> __device__ __forceinline__ void la_step(LA& st, const bf16x8 (&qf)[4], Frag& f, const char* kb, const VS& vs, const TP& t, const TP& n) {
;     f32x16 s = zero16();
; #pragma unroll
;     for (int d0 = 0; d0 < 4; ++d0) s = __builtin_amdgcn_mfma_f32_32x32x16_bf16(f.k[d0], qf[d0], s, 0, 0, 0);
;     la_loadK(f, kb, n);
;     float mx = NEGBIG;
; #pragma unroll
;     for (int r = 0; r < 16; ++r) { s[r] = MB::apply(t, r, s[r]); mx = __builtin_fmaxf(mx, s[r]); }
;     { auto rr = __builtin_amdgcn_permlane32_swap(__float_as_uint(mx), __float_as_uint(mx), false, false); mx = __builtin_fmaxf(__uint_as_float(rr[0]), __uint_as_float(rr[1])); }
;     if (__any(mx > st.m)) { const float mn = __builtin_fmaxf(st.m, mx), alpha = __builtin_amdgcn_exp2f(st.m - mn); st.m = mn; st.l *= alpha; st.o0 *= alpha; st.o1 *= alpha; }
.LBB0_690:
	v_add_u32_e32 v64, v159, v184
	v_lshl_or_b32 v64, v64, 7, s0
	v_add_lshl_u32 v64, v64, v164, 1
	v_ashrrev_i32_e32 v65, 31, v64
	v_lshl_add_u64 v[64:65], s[56:57], 0, v[64:65]
	v_add_co_u32_e32 v66, vcc, s80, v64
	v_add_u32_e32 v136, s24, v131
	s_nop 0
	v_addc_co_u32_e32 v67, vcc, 0, v65, vcc
	global_load_dwordx4 v[112:115], v[66:67], off offset:2560
	global_load_dwordx4 v[116:119], v[66:67], off offset:2048
	global_load_dwordx4 v[120:123], v[64:65], off offset:512
	global_load_dwordx4 v[124:127], v[64:65], off
	v_add_u32_e32 v132, 0x7120, v136
	s_waitcnt vmcnt(7)
	s_nop 0
	v_mfma_f32_32x32x16_bf16 v[64:79], v[96:99], v[80:83], 0
	s_waitcnt vmcnt(6)
	v_mfma_f32_32x32x16_bf16 v[64:79], v[104:107], v[84:87], v[64:79]
	s_waitcnt vmcnt(5)
	v_mfma_f32_32x32x16_bf16 v[64:79], v[100:103], v[88:91], v[64:79]
	s_waitcnt vmcnt(4)
	v_mfma_f32_32x32x16_bf16 v[64:79], v[108:111], v[92:95], v[64:79]
	global_load_dwordx4 v[96:99], v[128:129], off
	global_load_dwordx4 v[104:107], v[128:129], off offset:32
	global_load_dwordx4 v[100:103], v[128:129], off offset:64
	global_load_dwordx4 v[108:111], v[128:129], off offset:96
	ds_read2_b32 v[132:133], v132 offset1:1
	s_waitcnt lgkmcnt(0)
	s_nop 5
	v_add_f32_e32 v64, v64, v132
	v_cndmask_b32_e64 v132, v232, v64, s[6:7]
	v_add_f32_e32 v64, v65, v133
	v_add_u32_e32 v65, 0x7128, v136
	ds_read2_b32 v[134:135], v65 offset1:1
	v_cndmask_b32_e64 v64, v232, v64, s[8:9]
	v_max3_f32 v133, v132, s2, v64
	s_waitcnt lgkmcnt(0)
	v_add_f32_e32 v65, v66, v134
	v_cndmask_b32_e64 v66, v232, v65, s[10:11]
	v_add_f32_e32 v65, v67, v135
	v_add_u32_e32 v67, 0x7130, v136
	ds_read2_b32 v[134:135], v67 offset1:1
	v_cndmask_b32_e64 v65, v232, v65, s[12:13]
	v_max3_f32 v133, v133, v66, v65
	s_waitcnt lgkmcnt(0)
	v_add_f32_e32 v67, v68, v134
	v_cndmask_b32_e64 v68, v232, v67, s[14:15]
	v_add_f32_e32 v67, v69, v135
	v_add_u32_e32 v69, 0x7138, v136
	ds_read2_b32 v[134:135], v69 offset1:1
	v_cndmask_b32_e64 v67, v232, v67, s[16:17]
	v_max3_f32 v133, v133, v68, v67
	s_waitcnt lgkmcnt(0)
	v_add_f32_e32 v69, v70, v134
	v_cndmask_b32_e64 v70, v232, v69, s[18:19]
	v_add_f32_e32 v69, v71, v135
	v_add_u32_e32 v71, 0x7520, v136
	ds_read2_b32 v[134:135], v71 offset1:1
	v_cndmask_b32_e64 v69, v232, v69, s[20:21]
	v_max3_f32 v133, v133, v70, v69
	s_waitcnt lgkmcnt(0)
	v_add_f32_e32 v71, v72, v134
	v_cndmask_b32_e64 v72, v232, v71, s[6:7]
	v_add_f32_e32 v71, v73, v135
	v_add_u32_e32 v73, 0x7528, v136
	ds_read2_b32 v[134:135], v73 offset1:1
	v_cndmask_b32_e64 v71, v232, v71, s[8:9]
	v_max3_f32 v133, v133, v72, v71
	s_waitcnt lgkmcnt(0)
	v_add_f32_e32 v73, v74, v134
	v_cndmask_b32_e64 v74, v232, v73, s[10:11]
	v_add_f32_e32 v73, v75, v135
	v_add_u32_e32 v75, 0x7530, v136
	ds_read2_b32 v[134:135], v75 offset1:1
	v_cndmask_b32_e64 v73, v232, v73, s[12:13]
	v_max3_f32 v133, v133, v74, v73
	s_waitcnt lgkmcnt(0)
	v_add_f32_e32 v75, v76, v134
	v_cndmask_b32_e64 v76, v232, v75, s[14:15]
	v_add_f32_e32 v75, v77, v135
	v_add_u32_e32 v77, 0x7538, v136
	ds_read2_b32 v[134:135], v77 offset1:1
	v_cndmask_b32_e64 v75, v232, v75, s[16:17]
	v_max3_f32 v133, v133, v76, v75
	s_waitcnt lgkmcnt(0)
	v_add_f32_e32 v77, v78, v134
	v_cndmask_b32_e64 v78, v232, v77, s[18:19]
	v_add_f32_e32 v77, v79, v135
	v_cndmask_b32_e64 v77, v232, v77, s[20:21]
	v_max3_f32 v79, v133, v78, v77
	v_mov_b32_e32 v133, v79
	s_nop 1
	v_permlane32_swap_b32_e32 v79, v133
	v_max_f32_e32 v133, v133, v133
	v_max_f32_e32 v79, v79, v79
	v_max_f32_e32 v79, v79, v133
	v_cmp_gt_f32_e32 vcc, v79, v145
	s_cbranch_vccz .LBB0_692
	v_max_f32_e32 v79, v79, v79
	v_max_f32_e32 v133, v145, v145
	v_max_f32_e32 v79, v133, v79
	v_sub_f32_e32 v133, v145, v79
	v_exp_f32_e32 v134, v133
	v_mov_b32_e32 v145, v79
	v_mul_f32_e32 v156, v156, v134
	v_pk_mul_f32 v[30:31], v[30:31], v[134:135] op_sel_hi:[1,0]
	v_pk_mul_f32 v[28:29], v[28:29], v[134:135] op_sel_hi:[1,0]
	v_pk_mul_f32 v[26:27], v[26:27], v[134:135] op_sel_hi:[1,0]
	v_pk_mul_f32 v[24:25], v[24:25], v[134:135] op_sel_hi:[1,0]
	v_pk_mul_f32 v[22:23], v[22:23], v[134:135] op_sel_hi:[1,0]
	v_pk_mul_f32 v[20:21], v[20:21], v[134:135] op_sel_hi:[1,0]
	v_pk_mul_f32 v[18:19], v[18:19], v[134:135] op_sel_hi:[1,0]
	v_pk_mul_f32 v[16:17], v[16:17], v[134:135] op_sel_hi:[1,0]
	v_pk_mul_f32 v[14:15], v[14:15], v[134:135] op_sel_hi:[1,0]
	v_pk_mul_f32 v[12:13], v[12:13], v[134:135] op_sel_hi:[1,0]
	v_pk_mul_f32 v[10:11], v[10:11], v[134:135] op_sel_hi:[1,0]
	v_pk_mul_f32 v[8:9], v[8:9], v[134:135] op_sel_hi:[1,0]
	v_pk_mul_f32 v[6:7], v[6:7], v[134:135] op_sel_hi:[1,0]
	v_pk_mul_f32 v[4:5], v[4:5], v[134:135] op_sel_hi:[1,0]
	v_pk_mul_f32 v[2:3], v[2:3], v[134:135] op_sel_hi:[1,0]
	v_pk_mul_f32 v[0:1], v[0:1], v[134:135] op_sel_hi:[1,0]

; template <class MB, int V1, class VS> __device__ __forceinline__ void la_step(LA& st, const bf16x8 (&qf)[4], Frag& f, const char* kb, const VS& vs, const TP& t, const TP& n) {
;     f32x16 s = zero16();
; #pragma unroll
;     for (int d0 = 0; d0 < 4; ++d0) s = __builtin_amdgcn_mfma_f32_32x32x16_bf16(f.k[d0], qf[d0], s, 0, 0, 0);
;     la_loadK(f, kb, n);
;     float mx = NEGBIG;
; #pragma unroll
;     for (int r = 0; r < 16; ++r) { s[r] = MB::apply(t, r, s[r]); mx = __builtin_fmaxf(mx, s[r]); }
;     { auto rr = __builtin_amdgcn_permlane32_swap(__float_as_uint(mx), __float_as_uint(mx), false, false); mx = __builtin_fmaxf(__uint_as_float(rr[0]), __uint_as_float(rr[1])); }
;     if (__any(mx > st.m)) { const float mn = __builtin_fmaxf(st.m, mx), alpha = __builtin_amdgcn_exp2f(st.m - mn); st.m = mn; st.l *= alpha; st.o0 *= alpha; st.o1 *= alpha; }
.LBB0_696:
	v_lshlrev_b32_e32 v0, 1, v1
	v_ashrrev_i32_e32 v1, 31, v0
	v_lshl_add_u64 v[0:1], s[72:73], 0, v[0:1]
	v_add_co_u32_e32 v2, vcc, 0x100000, v0
	s_add_i32 s11, s1, s8
	s_nop 0
	v_addc_co_u32_e32 v3, vcc, 0, v1, vcc
	s_cmpk_lt_u32 s11, 0x400
	s_cselect_b64 vcc, -1, 0
	s_mov_b32 s10, s8
	s_and_b64 s[8:9], vcc, exec
	s_cselect_b32 s8, s11, s1
	global_load_dwordx4 v[64:67], v[2:3], off offset:2080
	global_load_dwordx4 v[68:71], v[2:3], off offset:2048
	global_load_dwordx4 v[72:75], v[0:1], off offset:32
	global_load_dwordx4 v[76:79], v[0:1], off
	v_lshl_add_u32 v0, s8, 6, v113
	s_add_i32 s8, s10, 32
	s_cmp_lg_u32 s10, 64
	s_cselect_b32 s9, s8, 64
	s_add_i32 s9, s9, s1
	s_cmpk_lt_u32 s9, 0x400
	v_add_u32_e32 v0, 0x4210, v0
	v_mov_b32_e32 v1, s53
	s_cselect_b32 s9, s9, s1
	v_cndmask_b32_e32 v118, v1, v0, vcc
	v_lshl_add_u32 v0, s9, 4, v112
	v_mul_lo_u32 v0, v0, s67
	v_add_lshl_u32 v114, v0, v181, 1
	s_nop 0
	s_waitcnt vmcnt(7)
	s_nop 0
	v_mfma_f32_32x32x16_bf16 v[0:15], v[60:63], v[80:83], 0
	s_waitcnt vmcnt(6)
	v_mfma_f32_32x32x16_bf16 v[0:15], v[56:59], v[88:91], v[0:15]
	s_waitcnt vmcnt(5)
	v_mfma_f32_32x32x16_bf16 v[0:15], v[52:55], v[96:99], v[0:15]
	s_waitcnt vmcnt(4)
	v_mfma_f32_32x32x16_bf16 v[0:15], v[48:51], v[104:107], v[0:15]
	global_load_dwordx4 v[60:63], v114, s[74:75]
	global_load_dwordx4 v[56:59], v114, s[74:75] offset:32
	global_load_dwordx4 v[52:55], v114, s[74:75] offset:64
	global_load_dwordx4 v[48:51], v114, s[74:75] offset:96
	ds_read2_b32 v[114:115], v118 offset1:16
	ds_read2_b32 v[116:117], v118 offset0:32 offset1:48
	s_waitcnt lgkmcnt(1)
	s_nop 4
	v_add_f32_e32 v114, v0, v114
	v_add_f32_e32 v0, v1, v115
	s_waitcnt lgkmcnt(0)
	v_add_f32_e32 v115, v2, v116
	v_add_f32_e32 v2, v3, v117
	ds_read2_b32 v[116:117], v118 offset0:64 offset1:80
	v_max3_f32 v1, v114, s2, v0
	v_max3_f32 v1, v1, v115, v2
	s_waitcnt lgkmcnt(0)
	v_add_f32_e32 v4, v4, v116
	v_add_f32_e32 v3, v5, v117
	ds_read2_b32 v[116:117], v118 offset0:96 offset1:112
	v_add_u32_e32 v118, 0x400, v118
	v_max3_f32 v1, v1, v4, v3
	s_waitcnt lgkmcnt(0)
	v_add_f32_e32 v6, v6, v116
	v_add_f32_e32 v5, v7, v117
	ds_read2_b32 v[116:117], v118 offset1:16
	v_max3_f32 v1, v1, v6, v5
	s_waitcnt lgkmcnt(0)
	v_add_f32_e32 v8, v8, v116
	v_add_f32_e32 v7, v9, v117
	ds_read2_b32 v[116:117], v118 offset0:32 offset1:48
	v_max3_f32 v1, v1, v8, v7
	s_waitcnt lgkmcnt(0)
	v_add_f32_e32 v10, v10, v116
	v_add_f32_e32 v9, v11, v117
	ds_read2_b32 v[116:117], v118 offset0:64 offset1:80
	v_max3_f32 v1, v1, v10, v9
	s_waitcnt lgkmcnt(0)
	v_add_f32_e32 v12, v12, v116
	v_add_f32_e32 v11, v13, v117
	ds_read2_b32 v[116:117], v118 offset0:96 offset1:112
	v_max3_f32 v1, v1, v12, v11
	s_waitcnt lgkmcnt(0)
	v_add_f32_e32 v14, v14, v116
	v_add_f32_e32 v13, v15, v117
	v_max3_f32 v1, v1, v14, v13
	v_mov_b32_e32 v15, v1
	s_nop 1
	v_permlane32_swap_b32_e32 v1, v15
	v_max_f32_e32 v15, v15, v15
	v_max_f32_e32 v1, v1, v1
	v_max_f32_e32 v1, v1, v15
	v_cmp_gt_f32_e32 vcc, v1, v145
	s_cbranch_vccz .LBB0_695
	v_max_f32_e32 v1, v1, v1
	v_max_f32_e32 v15, v145, v145
	v_max_f32_e32 v1, v15, v1
	v_sub_f32_e32 v15, v145, v1
	v_exp_f32_e32 v116, v15
	v_mov_b32_e32 v145, v1
	v_mul_f32_e32 v158, v158, v116
	v_pk_mul_f32 v[46:47], v[46:47], v[116:117] op_sel_hi:[1,0]
	v_pk_mul_f32 v[44:45], v[44:45], v[116:117] op_sel_hi:[1,0]
	v_pk_mul_f32 v[42:43], v[42:43], v[116:117] op_sel_hi:[1,0]
	v_pk_mul_f32 v[40:41], v[40:41], v[116:117] op_sel_hi:[1,0]
	v_pk_mul_f32 v[38:39], v[38:39], v[116:117] op_sel_hi:[1,0]
	v_pk_mul_f32 v[36:37], v[36:37], v[116:117] op_sel_hi:[1,0]
	v_pk_mul_f32 v[34:35], v[34:35], v[116:117] op_sel_hi:[1,0]
	v_pk_mul_f32 v[32:33], v[32:33], v[116:117] op_sel_hi:[1,0]
	v_pk_mul_f32 v[30:31], v[30:31], v[116:117] op_sel_hi:[1,0]
	v_pk_mul_f32 v[28:29], v[28:29], v[116:117] op_sel_hi:[1,0]
	v_pk_mul_f32 v[26:27], v[26:27], v[116:117] op_sel_hi:[1,0]
	v_pk_mul_f32 v[24:25], v[24:25], v[116:117] op_sel_hi:[1,0]
	v_pk_mul_f32 v[22:23], v[22:23], v[116:117] op_sel_hi:[1,0]
	v_pk_mul_f32 v[20:21], v[20:21], v[116:117] op_sel_hi:[1,0]
	v_pk_mul_f32 v[18:19], v[18:19], v[116:117] op_sel_hi:[1,0]
	v_pk_mul_f32 v[16:17], v[16:17], v[116:117] op_sel_hi:[1,0]
	s_branch .LBB0_695

; template <class MB, int V1, class VS> __device__ __forceinline__ void la_step(LA& st, const bf16x8 (&qf)[4], Frag& f, const char* kb, const VS& vs, const TP& t, const TP& n) {
;     f32x16 s = zero16();
; #pragma unroll
;     for (int d0 = 0; d0 < 4; ++d0) s = __builtin_amdgcn_mfma_f32_32x32x16_bf16(f.k[d0], qf[d0], s, 0, 0, 0);
;     la_loadK(f, kb, n);
;     float mx = NEGBIG;
; #pragma unroll
;     for (int r = 0; r < 16; ++r) { s[r] = MB::apply(t, r, s[r]); mx = __builtin_fmaxf(mx, s[r]); }
;     { auto rr = __builtin_amdgcn_permlane32_swap(__float_as_uint(mx), __float_as_uint(mx), false, false); mx = __builtin_fmaxf(__uint_as_float(rr[0]), __uint_as_float(rr[1])); }
;     if (__any(mx > st.m)) { const float mn = __builtin_fmaxf(st.m, mx), alpha = __builtin_amdgcn_exp2f(st.m - mn); st.m = mn; st.l *= alpha; st.o0 *= alpha; st.o1 *= alpha; }
.LBB0_700:
	v_lshlrev_b32_e32 v64, 1, v79
	v_ashrrev_i32_e32 v65, 31, v64
	v_lshl_add_u64 v[64:65], s[72:73], 0, v[64:65]
	s_mov_b32 s8, s4
	global_load_dwordx4 v[140:143], v[64:65], off
	global_load_dwordx4 v[136:139], v[64:65], off offset:32
	v_add_co_u32_e32 v64, vcc, s80, v64
	s_add_i32 s4, s1, s4
	s_nop 0
	v_addc_co_u32_e32 v65, vcc, 0, v65, vcc
	s_cmpk_lt_u32 s4, 0x400
	s_cselect_b64 vcc, -1, 0
	s_and_b64 s[6:7], vcc, exec
	s_cselect_b32 s4, s4, s1
	global_load_dwordx4 v[132:135], v[64:65], off offset:2048
	global_load_dwordx4 v[128:131], v[64:65], off offset:2080
	v_lshl_add_u32 v64, s4, 6, v161
	s_add_i32 s4, s8, 32
	s_cmp_lg_u32 s8, 64
	s_cselect_b32 s6, s4, 64
	s_add_i32 s6, s6, s1
	s_cmpk_lt_u32 s6, 0x400
	v_add_u32_e32 v64, 0x4210, v64
	v_mov_b32_e32 v65, s53
	s_cselect_b32 s6, s6, s1
	v_cndmask_b32_e32 v166, v65, v64, vcc
	v_lshl_add_u32 v64, s6, 4, v160
	v_mul_lo_u32 v64, v64, s67
	v_add_lshl_u32 v162, v64, v181, 1
	s_nop 0
	s_waitcnt vmcnt(7)
	s_nop 0
	v_mfma_f32_32x32x16_bf16 v[64:79], v[124:127], v[84:87], 0
	s_waitcnt vmcnt(6)
	v_mfma_f32_32x32x16_bf16 v[64:79], v[120:123], v[92:95], v[64:79]
	s_waitcnt vmcnt(5)
	v_mfma_f32_32x32x16_bf16 v[64:79], v[116:119], v[100:103], v[64:79]
	s_waitcnt vmcnt(4)
	v_mfma_f32_32x32x16_bf16 v[64:79], v[112:115], v[108:111], v[64:79]
	global_load_dwordx4 v[124:127], v162, s[74:75]
	global_load_dwordx4 v[120:123], v162, s[74:75] offset:32
	global_load_dwordx4 v[116:119], v162, s[74:75] offset:64
	global_load_dwordx4 v[112:115], v162, s[74:75] offset:96
	ds_read2_b32 v[162:163], v166 offset1:16
	ds_read2_b32 v[164:165], v166 offset0:32 offset1:48
	s_waitcnt lgkmcnt(1)
	s_nop 4
	v_add_f32_e32 v162, v64, v162
	v_add_f32_e32 v64, v65, v163
	s_waitcnt lgkmcnt(0)
	v_add_f32_e32 v66, v66, v164
	v_add_f32_e32 v65, v67, v165
	ds_read2_b32 v[164:165], v166 offset0:64 offset1:80
	v_max3_f32 v163, v162, s2, v64
	v_max3_f32 v163, v163, v66, v65
	s_waitcnt lgkmcnt(0)
	v_add_f32_e32 v68, v68, v164
	v_add_f32_e32 v67, v69, v165
	ds_read2_b32 v[164:165], v166 offset0:96 offset1:112
	v_add_u32_e32 v166, 0x400, v166
	v_max3_f32 v163, v163, v68, v67
	s_waitcnt lgkmcnt(0)
	v_add_f32_e32 v70, v70, v164
	v_add_f32_e32 v69, v71, v165
	ds_read2_b32 v[164:165], v166 offset1:16
	v_max3_f32 v163, v163, v70, v69
	s_waitcnt lgkmcnt(0)
	v_add_f32_e32 v72, v72, v164
	v_add_f32_e32 v71, v73, v165
	ds_read2_b32 v[164:165], v166 offset0:32 offset1:48
	v_max3_f32 v163, v163, v72, v71
	s_waitcnt lgkmcnt(0)
	v_add_f32_e32 v74, v74, v164
	v_add_f32_e32 v73, v75, v165
	ds_read2_b32 v[164:165], v166 offset0:64 offset1:80
	v_max3_f32 v163, v163, v74, v73
	s_waitcnt lgkmcnt(0)
	v_add_f32_e32 v76, v76, v164
	v_add_f32_e32 v75, v77, v165
	ds_read2_b32 v[164:165], v166 offset0:96 offset1:112
	v_max3_f32 v163, v163, v76, v75
	s_waitcnt lgkmcnt(0)
	v_add_f32_e32 v78, v78, v164
	v_add_f32_e32 v77, v79, v165
	v_max3_f32 v79, v163, v78, v77
	v_mov_b32_e32 v163, v79
	s_nop 1
	v_permlane32_swap_b32_e32 v79, v163
	v_max_f32_e32 v163, v163, v163
	v_max_f32_e32 v79, v79, v79
	v_max_f32_e32 v79, v79, v163
	v_cmp_gt_f32_e32 vcc, v79, v149
	s_cbranch_vccz .LBB0_699
	v_max_f32_e32 v79, v79, v79
	v_max_f32_e32 v163, v149, v149
	v_max_f32_e32 v79, v163, v79
	v_sub_f32_e32 v149, v149, v79
	v_exp_f32_e32 v164, v149
	v_mov_b32_e32 v149, v79
	v_mul_f32_e32 v156, v156, v164
	v_pk_mul_f32 v[62:63], v[62:63], v[164:165] op_sel_hi:[1,0]
	v_pk_mul_f32 v[60:61], v[60:61], v[164:165] op_sel_hi:[1,0]
	v_pk_mul_f32 v[58:59], v[58:59], v[164:165] op_sel_hi:[1,0]
	v_pk_mul_f32 v[56:57], v[56:57], v[164:165] op_sel_hi:[1,0]
	v_pk_mul_f32 v[54:55], v[54:55], v[164:165] op_sel_hi:[1,0]
	v_pk_mul_f32 v[52:53], v[52:53], v[164:165] op_sel_hi:[1,0]
	v_pk_mul_f32 v[50:51], v[50:51], v[164:165] op_sel_hi:[1,0]
	v_pk_mul_f32 v[48:49], v[48:49], v[164:165] op_sel_hi:[1,0]
	v_pk_mul_f32 v[14:15], v[14:15], v[164:165] op_sel_hi:[1,0]
	v_pk_mul_f32 v[12:13], v[12:13], v[164:165] op_sel_hi:[1,0]
	v_pk_mul_f32 v[10:11], v[10:11], v[164:165] op_sel_hi:[1,0]
	v_pk_mul_f32 v[8:9], v[8:9], v[164:165] op_sel_hi:[1,0]
	v_pk_mul_f32 v[6:7], v[6:7], v[164:165] op_sel_hi:[1,0]
	v_pk_mul_f32 v[4:5], v[4:5], v[164:165] op_sel_hi:[1,0]
	v_pk_mul_f32 v[2:3], v[2:3], v[164:165] op_sel_hi:[1,0]
	v_pk_mul_f32 v[0:1], v[0:1], v[164:165] op_sel_hi:[1,0]
	s_branch .LBB0_699

; template <class MB> __device__ __forceinline__ void la_soft(LA& st, f32x16& s, const TP& t, bf16x8& pf0, bf16x8& pf1) {
;     float mx = NEGBIG;
; #pragma unroll
;     for (int r = 0; r < 16; ++r) { s[r] = MB::apply(t, r, s[r]); mx = __builtin_fmaxf(mx, s[r]); }
;     { auto rr = __builtin_amdgcn_permlane32_swap(__float_as_uint(mx), __float_as_uint(mx), false, false); mx = __builtin_fmaxf(__uint_as_float(rr[0]), __uint_as_float(rr[1])); }
;     if (__any(mx > st.m)) { const float mn = __builtin_fmaxf(st.m, mx), alpha = __builtin_amdgcn_exp2f(st.m - mn); st.m = mn; st.l *= alpha; st.o0 *= alpha; st.o1 *= alpha; }
; template <class MB, int V1, class VS> __device__ __forceinline__ void la_step2(LA& sa, LA& sb, const bf16x8 (&qa)[4], const bf16x8 (&qb)[4], Frag& f, const char* kb, const VS& vs, const TP& t, const TP& n) {
;     bf16x8 pa0, pa1;
;     { f32x16 s0 = zero16();
; #pragma unroll
;       for (int d0 = 0; d0 < 4; ++d0) s0 = __builtin_amdgcn_mfma_f32_32x32x16_bf16(f.k[d0], qa[d0], s0, 0, 0, 0);
;       la_soft<MB>(sa, s0, t, pa0, pa1); }
.LBB0_704:
	v_or_b32_e32 v64, v64, v147
	v_lshlrev_b32_e32 v64, 1, v64
	v_ashrrev_i32_e32 v65, 31, v64
	v_lshl_add_u64 v[64:65], s[72:73], 0, v[64:65]
	global_load_dwordx4 v[140:143], v[64:65], off
	global_load_dwordx4 v[132:135], v[64:65], off offset:96
	v_add_co_u32_e32 v64, vcc, s80, v64
	s_and_b32 s5, s10, 32
	s_nop 0
	v_addc_co_u32_e32 v65, vcc, 0, v65, vcc
	s_and_b32 s4, s8, 12
	s_add_i32 s6, s1, s5
	global_load_dwordx4 v[136:139], v[64:65], off offset:2048
	global_load_dwordx4 v[128:131], v[64:65], off offset:2144
	v_lshl_add_u32 v64, s4, 2, v154
	s_lshl_b32 s4, s6, 6
	v_add_u32_e32 v159, s4, v64
	v_add_u32_e32 v155, 0x1800, v159
	ds_read2_b32 v[160:161], v155 offset0:128 offset1:144
	s_cmpk_lt_i32 s6, 0x3e1
	s_waitcnt vmcnt(7)
	v_mfma_f32_32x32x16_bf16 v[64:79], v[124:127], v[80:83], 0
	s_cselect_b64 s[4:5], -1, 0
	s_cmp_gt_i32 s6, -1
	s_cselect_b64 s[6:7], -1, 0
	v_add_u32_e32 v159, 0x1c00, v159
	s_waitcnt vmcnt(6)
	v_mfma_f32_32x32x16_bf16 v[64:79], v[120:123], v[88:91], v[64:79]
	s_waitcnt vmcnt(5)
	v_mfma_f32_32x32x16_bf16 v[64:79], v[116:119], v[96:99], v[64:79]
	s_waitcnt vmcnt(4)
	v_mfma_f32_32x32x16_bf16 v[64:79], v[112:115], v[104:107], v[64:79]
	s_waitcnt lgkmcnt(0)
	s_nop 10
	v_add_f32_e32 v64, v64, v160
	v_cndmask_b32_e64 v160, v232, v64, s[6:7]
	v_add_f32_e32 v64, v65, v161
	v_cndmask_b32_e64 v161, v232, v64, s[6:7]
	ds_read2_b32 v[64:65], v155 offset0:160 offset1:176
	v_max3_f32 v164, v160, s2, v161
	s_waitcnt lgkmcnt(0)
	v_add_f32_e32 v64, v66, v64
	v_cndmask_b32_e64 v162, v232, v64, s[6:7]
	v_add_f32_e32 v64, v67, v65
	v_cndmask_b32_e64 v163, v232, v64, s[6:7]
	ds_read2_b32 v[64:65], v155 offset0:192 offset1:208
	v_max3_f32 v66, v164, v162, v163
	s_waitcnt lgkmcnt(0)
	v_add_f32_e32 v64, v68, v64
	v_cndmask_b32_e64 v164, v232, v64, s[6:7]
	v_add_f32_e32 v64, v69, v65
	v_cndmask_b32_e64 v165, v232, v64, s[6:7]
	ds_read2_b32 v[64:65], v155 offset0:224 offset1:240
	v_max3_f32 v66, v66, v164, v165
	s_waitcnt lgkmcnt(0)
	v_add_f32_e32 v64, v70, v64
	v_cndmask_b32_e64 v167, v232, v64, s[6:7]
	v_add_f32_e32 v64, v71, v65
	v_cndmask_b32_e64 v166, v232, v64, s[6:7]
	ds_read2_b32 v[64:65], v159 offset0:128 offset1:144
	v_max3_f32 v66, v66, v167, v166
	s_waitcnt lgkmcnt(0)
	v_add_f32_e32 v64, v72, v64
	v_cndmask_b32_e64 v168, v232, v64, s[4:5]
	v_add_f32_e32 v64, v73, v65
	v_cndmask_b32_e64 v169, v232, v64, s[4:5]
	ds_read2_b32 v[64:65], v159 offset0:160 offset1:176
	v_max3_f32 v66, v66, v168, v169
	s_waitcnt lgkmcnt(0)
	v_add_f32_e32 v64, v74, v64
	v_cndmask_b32_e64 v171, v232, v64, s[4:5]
	v_add_f32_e32 v64, v75, v65
	v_cndmask_b32_e64 v170, v232, v64, s[4:5]
	ds_read2_b32 v[64:65], v159 offset0:192 offset1:208
	v_max3_f32 v66, v66, v171, v170
	s_waitcnt lgkmcnt(0)
	v_add_f32_e32 v64, v76, v64
	v_cndmask_b32_e64 v172, v232, v64, s[4:5]
	v_add_f32_e32 v64, v77, v65
	v_cndmask_b32_e64 v173, v232, v64, s[4:5]
	ds_read2_b32 v[64:65], v159 offset0:224 offset1:240
	v_max3_f32 v66, v66, v172, v173
	s_waitcnt lgkmcnt(0)
	v_add_f32_e32 v64, v78, v64
	v_cndmask_b32_e64 v174, v232, v64, s[4:5]
	v_add_f32_e32 v64, v79, v65
	v_cndmask_b32_e64 v175, v232, v64, s[4:5]
	v_max3_f32 v64, v66, v174, v175
	v_mov_b32_e32 v65, v64
	s_nop 1
	v_permlane32_swap_b32_e32 v64, v65
	v_max_f32_e32 v65, v65, v65
	v_max_f32_e32 v64, v64, v64
	v_max_f32_e32 v64, v64, v65
	v_cmp_gt_f32_e32 vcc, v64, v145
	s_cbranch_vccz .LBB0_706
	v_max_f32_e32 v64, v64, v64
	v_max_f32_e32 v65, v145, v145
	v_max_f32_e32 v65, v65, v64
	v_sub_f32_e32 v64, v145, v65
	v_exp_f32_e32 v64, v64
	v_mov_b32_e32 v145, v65
	v_mul_f32_e32 v158, v158, v64
	v_pk_mul_f32 v[46:47], v[46:47], v[64:65] op_sel_hi:[1,0]
	v_pk_mul_f32 v[44:45], v[44:45], v[64:65] op_sel_hi:[1,0]
	v_pk_mul_f32 v[42:43], v[42:43], v[64:65] op_sel_hi:[1,0]
	v_pk_mul_f32 v[40:41], v[40:41], v[64:65] op_sel_hi:[1,0]
	v_pk_mul_f32 v[38:39], v[38:39], v[64:65] op_sel_hi:[1,0]
	v_pk_mul_f32 v[36:37], v[36:37], v[64:65] op_sel_hi:[1,0]
	v_pk_mul_f32 v[34:35], v[34:35], v[64:65] op_sel_hi:[1,0]
	v_pk_mul_f32 v[32:33], v[32:33], v[64:65] op_sel_hi:[1,0]
	v_pk_mul_f32 v[30:31], v[30:31], v[64:65] op_sel_hi:[1,0]
	v_pk_mul_f32 v[28:29], v[28:29], v[64:65] op_sel_hi:[1,0]
	v_pk_mul_f32 v[26:27], v[26:27], v[64:65] op_sel_hi:[1,0]
	v_pk_mul_f32 v[24:25], v[24:25], v[64:65] op_sel_hi:[1,0]
	v_pk_mul_f32 v[22:23], v[22:23], v[64:65] op_sel_hi:[1,0]
	v_pk_mul_f32 v[20:21], v[20:21], v[64:65] op_sel_hi:[1,0]
	v_pk_mul_f32 v[18:19], v[18:19], v[64:65] op_sel_hi:[1,0]
	v_pk_mul_f32 v[16:17], v[16:17], v[64:65] op_sel_hi:[1,0]
; #define LAS __attribute__((address_space(3)))
; __host__ __device__ __forceinline__ int vt_off(int d, int p) { return (d >> 1) * VTPP + (p >> 5) * 64 + (d & 1) * 32 + (p & 31); }
; template <class MB, int V1, class VS> __device__ __forceinline__ void la_step2(LA& sa, LA& sb, const bf16x8 (&qa)[4], const bf16x8 (&qb)[4], Frag& f, const char* kb, const VS& vs, const TP& t, const TP& n) {
;     ...
;     f32x16 s1 = zero16();
; #pragma unroll
;     for (int d0 = 0; d0 < 4; ++d0) s1 = __builtin_amdgcn_mfma_f32_32x32x16_bf16(f.k[d0], qb[d0], s1, 0, 0, 0);
;     la_loadK(f, kb, n);
;     sa.o0 = __builtin_amdgcn_mfma_f32_32x32x16_bf16(f.v[0], pa0, sa.o0, 0, 0, 0); sa.o1 = __builtin_amdgcn_mfma_f32_32x32x16_bf16(f.v[2], pa0, sa.o1, 0, 0, 0);
;     sa.o0 = __builtin_amdgcn_mfma_f32_32x32x16_bf16(f.v[1], pa1, sa.o0, 0, 0, 0); sa.o1 = __builtin_amdgcn_mfma_f32_32x32x16_bf16(f.v[3], pa1, sa.o1, 0, 0, 0);
;     { bf16x8 pb0, pb1; const TP tb = MB::second(t);
;       la_soft<MB>(sb, s1, tb, pb0, pb1);
;       sb.o0 = __builtin_amdgcn_mfma_f32_32x32x16_bf16(f.v[0], pb0, sb.o0, 0, 0, 0); sb.o1 = __builtin_amdgcn_mfma_f32_32x32x16_bf16(f.v[2], pb0, sb.o1, 0, 0, 0);
;       sb.o0 = __builtin_amdgcn_mfma_f32_32x32x16_bf16(f.v[1], pb1, sb.o0, 0, 0, 0); sb.o1 = __builtin_amdgcn_mfma_f32_32x32x16_bf16(f.v[3], pb1, sb.o1, 0, 0, 0); }
; __global__ void __launch_bounds__(NWAVES * 64, 2) mk_fwd(Args args) {
;     ...
;                 auto t4 = [&](int i) -> TP { const int cq = (cA & 3) + 4 * (i >> 1), sb_ = s0 - 16 + 32 * (i & 1);
;                     const int t0 = 16 * sb_ + cq; int tk = t0 + (lam & 7) * 16 + (lam >> 3) * 128; tk = tk < 0 ? 0 : (tk > SEQ - 1 ? SEQ - 1 : tk); TP t;
;                     t.koff = ((unsigned)tk * PP + kc) * 2u; t.voff = (unsigned)(vt_off(vd, cq * 1024 + sb_ + 8 * hi) * 2);
;                     t.tp = (const LAS char*)(tabD4 + (1024 + t0 + hi * 128 - tqa)); t.tp2 = t.tp - 16; t.cb = (sb_ < 0 ? 1 : 0) | (sb_ + 32 > 1024 ? 2 : 0); return t; };
.LBB0_706:
	s_cmpk_lg_i32 s10, 0xe0
	s_cselect_b32 s12, s9, 7
	s_lshl_b32 s11, s12, 1
	s_lshl_b32 s12, s12, 5
	s_and_b32 s12, s12, 32
	s_and_b32 s11, s11, 28
	s_add_i32 s12, s1, s12
	s_or_b32 s11, s11, s0
	s_lshl_b32 s13, s12, 4
	s_add_i32 s13, s13, s11
	v_add_u32_e32 v64, s13, v157
	v_med3_i32 v64, v64, 0, v254
	v_mul_u32_u24_e32 v64, 0x1a40, v64
	v_add_lshl_u32 v180, v64, v181, 1
	s_nop 0
	s_nop 1
	v_mfma_f32_32x32x16_bf16 v[64:79], v[124:127], v[84:87], 0
	v_sub_f32_e32 v124, v160, v145
	v_exp_f32_e32 v160, v124
	v_sub_f32_e32 v124, v161, v145
	v_exp_f32_e32 v161, v124
	v_sub_f32_e32 v124, v162, v145
	v_exp_f32_e32 v162, v124
	v_sub_f32_e32 v124, v163, v145
	v_mfma_f32_32x32x16_bf16 v[64:79], v[120:123], v[92:95], v[64:79]
	v_sub_f32_e32 v120, v164, v145
	v_exp_f32_e32 v164, v120
	v_sub_f32_e32 v120, v165, v145
	v_exp_f32_e32 v165, v120
	v_sub_f32_e32 v120, v167, v145
	v_exp_f32_e32 v163, v124
	v_exp_f32_e32 v167, v120
	v_mfma_f32_32x32x16_bf16 v[64:79], v[116:119], v[100:103], v[64:79]
	v_sub_f32_e32 v116, v166, v145
	v_exp_f32_e32 v166, v116
	v_sub_f32_e32 v116, v168, v145
	v_exp_f32_e32 v168, v116
	v_sub_f32_e32 v116, v169, v145
	v_exp_f32_e32 v169, v116
	v_sub_f32_e32 v116, v171, v145
	v_exp_f32_e32 v171, v116
	v_sub_f32_e32 v116, v172, v145
	v_exp_f32_e32 v172, v116
	v_sub_f32_e32 v116, v173, v145
	v_mfma_f32_32x32x16_bf16 v[64:79], v[112:115], v[108:111], v[64:79]
	v_sub_f32_e32 v112, v170, v145
	v_exp_f32_e32 v173, v116
	v_sub_f32_e32 v116, v174, v145
	v_exp_f32_e32 v170, v112
	v_cvt_pk_bf16_f32 v112, v160, v161
	v_cvt_pk_bf16_f32 v113, v162, v163
	v_cvt_pk_bf16_f32 v114, v164, v165
	v_cvt_pk_bf16_f32 v115, v167, v166
	v_exp_f32_e32 v174, v116
	v_sub_f32_e32 v116, v175, v145
	s_waitcnt vmcnt(3)
	v_mfma_f32_32x32x16_bf16 v[32:47], v[140:143], v[112:115], v[32:47]
	v_exp_f32_e32 v175, v116
	global_load_dwordx4 v[124:127], v180, s[74:75]
	global_load_dwordx4 v[120:123], v180, s[74:75] offset:32
	v_cvt_pk_bf16_f32 v176, v168, v169
	v_cvt_pk_bf16_f32 v177, v171, v170
	v_cvt_pk_bf16_f32 v178, v172, v173
	v_cvt_pk_bf16_f32 v179, v174, v175
	s_waitcnt vmcnt(3)
	v_mfma_f32_32x32x16_bf16 v[16:31], v[136:139], v[112:115], v[16:31]
	global_load_dwordx4 v[116:119], v180, s[74:75] offset:64
	global_load_dwordx4 v[112:115], v180, s[74:75] offset:96
	ds_read2_b32 v[182:183], v155 offset0:124 offset1:140
	ds_read2_b32 v[184:185], v159 offset0:220 offset1:236
	s_waitcnt lgkmcnt(1)
	v_add_f32_e32 v64, v64, v182
	v_mfma_f32_32x32x16_bf16 v[32:47], v[132:135], v[176:179], v[32:47]
	s_waitcnt vmcnt(4)
	v_mfma_f32_32x32x16_bf16 v[16:31], v[128:131], v[176:179], v[16:31]
	ds_read2_b32 v[178:179], v155 offset0:156 offset1:172
	v_cndmask_b32_e64 v176, v232, v64, s[6:7]
	v_add_f32_e32 v64, v65, v183
	ds_read2_b32 v[182:183], v155 offset0:188 offset1:204
	v_cndmask_b32_e64 v64, v232, v64, s[6:7]
	s_waitcnt lgkmcnt(1)
	v_add_f32_e32 v66, v66, v178
	v_cndmask_b32_e64 v178, v232, v66, s[6:7]
	v_add_f32_e32 v66, v67, v179
	v_cndmask_b32_e64 v177, v232, v66, s[6:7]
	ds_read2_b32 v[66:67], v155 offset0:220 offset1:236
	s_waitcnt lgkmcnt(1)
	v_add_f32_e32 v68, v68, v182
	v_cndmask_b32_e64 v155, v232, v68, s[6:7]
	v_add_f32_e32 v68, v69, v183
	ds_read2_b32 v[182:183], v159 offset0:124 offset1:140
	s_waitcnt lgkmcnt(1)
	v_add_f32_e32 v66, v70, v66
	v_cndmask_b32_e64 v70, v232, v66, s[6:7]
	v_add_f32_e32 v66, v71, v67
	v_cndmask_b32_e64 v69, v232, v66, s[6:7]
	ds_read2_b32 v[66:67], v159 offset0:156 offset1:172
	s_waitcnt lgkmcnt(1)
	v_add_f32_e32 v71, v72, v182
	v_cndmask_b32_e64 v72, v232, v71, s[4:5]
	v_add_f32_e32 v71, v73, v183
	ds_read2_b32 v[182:183], v159 offset0:188 offset1:204
	v_max3_f32 v65, v176, s2, v64
	v_max3_f32 v65, v65, v178, v177
	v_cndmask_b32_e64 v68, v232, v68, s[6:7]
	s_waitcnt lgkmcnt(1)
	v_add_f32_e32 v66, v74, v66
	v_max3_f32 v65, v65, v155, v68
	v_cndmask_b32_e64 v74, v232, v66, s[4:5]
	v_add_f32_e32 v66, v75, v67
	v_max3_f32 v65, v65, v70, v69
	v_cndmask_b32_e64 v71, v232, v71, s[4:5]
	v_cndmask_b32_e64 v73, v232, v66, s[4:5]
	s_waitcnt lgkmcnt(0)
	v_add_f32_e32 v66, v76, v182
	v_max3_f32 v65, v65, v72, v71
	v_cndmask_b32_e64 v75, v232, v66, s[4:5]
	v_add_f32_e32 v66, v77, v183
	v_max3_f32 v65, v65, v74, v73
	v_cndmask_b32_e64 v67, v232, v66, s[4:5]
	v_max3_f32 v76, v65, v75, v67
	v_add_f32_e32 v65, v78, v184
	v_cndmask_b32_e64 v66, v232, v65, s[4:5]
	v_add_f32_e32 v65, v79, v185
	v_cndmask_b32_e64 v65, v232, v65, s[4:5]
	v_max3_f32 v76, v76, v66, v65
	v_mov_b32_e32 v77, v76
	s_nop 1
	v_permlane32_swap_b32_e32 v76, v77
	v_max_f32_e32 v77, v77, v77
	v_max_f32_e32 v76, v76, v76
	v_max_f32_e32 v76, v76, v77
	v_cmp_gt_f32_e32 vcc, v76, v149
	s_cbranch_vccz .LBB0_703
	v_max_f32_e32 v76, v76, v76
	v_max_f32_e32 v77, v149, v149
	v_max_f32_e32 v77, v77, v76
	v_sub_f32_e32 v76, v149, v77
	v_exp_f32_e32 v76, v76
	v_mov_b32_e32 v149, v77
	v_mul_f32_e32 v156, v156, v76
	v_pk_mul_f32 v[62:63], v[62:63], v[76:77] op_sel_hi:[1,0]
	v_pk_mul_f32 v[60:61], v[60:61], v[76:77] op_sel_hi:[1,0]
	v_pk_mul_f32 v[58:59], v[58:59], v[76:77] op_sel_hi:[1,0]
	v_pk_mul_f32 v[56:57], v[56:57], v[76:77] op_sel_hi:[1,0]
	v_pk_mul_f32 v[54:55], v[54:55], v[76:77] op_sel_hi:[1,0]
	v_pk_mul_f32 v[52:53], v[52:53], v[76:77] op_sel_hi:[1,0]
	v_pk_mul_f32 v[50:51], v[50:51], v[76:77] op_sel_hi:[1,0]
	v_pk_mul_f32 v[48:49], v[48:49], v[76:77] op_sel_hi:[1,0]
	v_pk_mul_f32 v[14:15], v[14:15], v[76:77] op_sel_hi:[1,0]
	v_pk_mul_f32 v[12:13], v[12:13], v[76:77] op_sel_hi:[1,0]
	v_pk_mul_f32 v[10:11], v[10:11], v[76:77] op_sel_hi:[1,0]
	v_pk_mul_f32 v[8:9], v[8:9], v[76:77] op_sel_hi:[1,0]
	v_pk_mul_f32 v[6:7], v[6:7], v[76:77] op_sel_hi:[1,0]
	v_pk_mul_f32 v[4:5], v[4:5], v[76:77] op_sel_hi:[1,0]
	v_pk_mul_f32 v[2:3], v[2:3], v[76:77] op_sel_hi:[1,0]
	v_pk_mul_f32 v[0:1], v[0:1], v[76:77] op_sel_hi:[1,0]
	s_branch .LBB0_703
